# S5 operator staging loops and adaLN GEMV (phase 0): serialized load/wait chains replaced by all-loads-first / 48-deep register ring (same arithmetic order)
# speedup vs baseline: 1.0152x; 1.0059x over previous
; __device__ __forceinline__ int tid_opaque() { int t = threadIdx.x; asm volatile("" : "+v"(t)); return t; }
; __device__ __forceinline__ float siluf_(float x) { return x * __builtin_amdgcn_rcpf(1.0f + __expf(-x)); }
; __device__ __forceinline__ void mod_item(PREF P, int l, int nt, float* sm) {
;     const int tid = tid_opaque(); float* sc = sm; float* red = sm + 3 * 2048;
;     for (int i = tid; i < 3 * 2048; i += 512) { const int r = i >> 11, k = i & 2047; const float v = r < 2 ? P.c[r * 2048 + k] : P.c_ctx[k]; sc[i] = siluf_(v); }
;     __syncthreads();
.LBB0_98:
	v_and_b32_e32 v6, 0x7ff, v3
	v_lshlrev_b32_e32 v22, 2, v6
	v_lshl_add_u64 v[6:7], s[20:21], 0, v[22:23]
	v_cmp_gt_i32_e32 vcc, s93, v3
	s_movk_i32 s9, 0x15ff
	s_mov_b64 s[52:53], 0x800
	v_cndmask_b32_e32 v7, v7, v5, vcc
	v_cndmask_b32_e32 v6, v6, v4, vcc
	global_load_dword v124, v[6:7], off
	v_add_u32_e32 v3, 0x200, v3
	v_lshl_add_u64 v[4:5], v[4:5], 0, s[52:53]
	v_and_b32_e32 v6, 0x7ff, v3
	v_lshlrev_b32_e32 v22, 2, v6
	v_lshl_add_u64 v[6:7], s[20:21], 0, v[22:23]
	v_cmp_gt_i32_e32 vcc, s93, v3
	s_movk_i32 s9, 0x15ff
	s_mov_b64 s[52:53], 0x800
	v_cndmask_b32_e32 v7, v7, v5, vcc
	v_cndmask_b32_e32 v6, v6, v4, vcc
	global_load_dword v125, v[6:7], off
	v_add_u32_e32 v3, 0x200, v3
	v_lshl_add_u64 v[4:5], v[4:5], 0, s[52:53]
	v_and_b32_e32 v6, 0x7ff, v3
	v_lshlrev_b32_e32 v22, 2, v6
	v_lshl_add_u64 v[6:7], s[20:21], 0, v[22:23]
	v_cmp_gt_i32_e32 vcc, s93, v3
	s_movk_i32 s9, 0x15ff
	s_mov_b64 s[52:53], 0x800
	v_cndmask_b32_e32 v7, v7, v5, vcc
	v_cndmask_b32_e32 v6, v6, v4, vcc
	global_load_dword v126, v[6:7], off
	v_add_u32_e32 v3, 0x200, v3
	v_lshl_add_u64 v[4:5], v[4:5], 0, s[52:53]
	v_and_b32_e32 v6, 0x7ff, v3
	v_lshlrev_b32_e32 v22, 2, v6
	v_lshl_add_u64 v[6:7], s[20:21], 0, v[22:23]
	v_cmp_gt_i32_e32 vcc, s93, v3
	s_movk_i32 s9, 0x15ff
	s_mov_b64 s[52:53], 0x800
	v_cndmask_b32_e32 v7, v7, v5, vcc
	v_cndmask_b32_e32 v6, v6, v4, vcc
	global_load_dword v127, v[6:7], off
	v_add_u32_e32 v3, 0x200, v3
	v_lshl_add_u64 v[4:5], v[4:5], 0, s[52:53]
	v_and_b32_e32 v6, 0x7ff, v3
	v_lshlrev_b32_e32 v22, 2, v6
	v_lshl_add_u64 v[6:7], s[20:21], 0, v[22:23]
	v_cmp_gt_i32_e32 vcc, s93, v3
	s_movk_i32 s9, 0x15ff
	s_mov_b64 s[52:53], 0x800
	v_cndmask_b32_e32 v7, v7, v5, vcc
	v_cndmask_b32_e32 v6, v6, v4, vcc
	global_load_dword v128, v[6:7], off
	v_add_u32_e32 v3, 0x200, v3
	v_lshl_add_u64 v[4:5], v[4:5], 0, s[52:53]
	v_and_b32_e32 v6, 0x7ff, v3
	v_lshlrev_b32_e32 v22, 2, v6
	v_lshl_add_u64 v[6:7], s[20:21], 0, v[22:23]
	v_cmp_gt_i32_e32 vcc, s93, v3
	s_movk_i32 s9, 0x15ff
	s_mov_b64 s[52:53], 0x800
	v_cndmask_b32_e32 v7, v7, v5, vcc
	v_cndmask_b32_e32 v6, v6, v4, vcc
	global_load_dword v129, v[6:7], off
	v_add_u32_e32 v3, 0x200, v3
	v_lshl_add_u64 v[4:5], v[4:5], 0, s[52:53]
	v_and_b32_e32 v6, 0x7ff, v3
	v_lshlrev_b32_e32 v22, 2, v6
	v_lshl_add_u64 v[6:7], s[20:21], 0, v[22:23]
	v_cmp_gt_i32_e32 vcc, s93, v3
	s_movk_i32 s9, 0x15ff
	s_mov_b64 s[52:53], 0x800
	v_cndmask_b32_e32 v7, v7, v5, vcc
	v_cndmask_b32_e32 v6, v6, v4, vcc
	global_load_dword v130, v[6:7], off
	v_add_u32_e32 v3, 0x200, v3
	v_lshl_add_u64 v[4:5], v[4:5], 0, s[52:53]
	v_and_b32_e32 v6, 0x7ff, v3
	v_lshlrev_b32_e32 v22, 2, v6
	v_lshl_add_u64 v[6:7], s[20:21], 0, v[22:23]
	v_cmp_gt_i32_e32 vcc, s93, v3
	s_movk_i32 s9, 0x15ff
	s_mov_b64 s[52:53], 0x800
	v_cndmask_b32_e32 v7, v7, v5, vcc
	v_cndmask_b32_e32 v6, v6, v4, vcc
	global_load_dword v131, v[6:7], off
	v_add_u32_e32 v3, 0x200, v3
	v_lshl_add_u64 v[4:5], v[4:5], 0, s[52:53]
	v_and_b32_e32 v6, 0x7ff, v3
	v_lshlrev_b32_e32 v22, 2, v6
	v_lshl_add_u64 v[6:7], s[20:21], 0, v[22:23]
	v_cmp_gt_i32_e32 vcc, s93, v3
	s_movk_i32 s9, 0x15ff
	s_mov_b64 s[52:53], 0x800
	v_cndmask_b32_e32 v7, v7, v5, vcc
	v_cndmask_b32_e32 v6, v6, v4, vcc
	global_load_dword v132, v[6:7], off
	v_add_u32_e32 v3, 0x200, v3
	v_lshl_add_u64 v[4:5], v[4:5], 0, s[52:53]
	v_and_b32_e32 v6, 0x7ff, v3
	v_lshlrev_b32_e32 v22, 2, v6
	v_lshl_add_u64 v[6:7], s[20:21], 0, v[22:23]
	v_cmp_gt_i32_e32 vcc, s93, v3
	s_movk_i32 s9, 0x15ff
	s_mov_b64 s[52:53], 0x800
	v_cndmask_b32_e32 v7, v7, v5, vcc
	v_cndmask_b32_e32 v6, v6, v4, vcc
	global_load_dword v133, v[6:7], off
	v_add_u32_e32 v3, 0x200, v3
	v_lshl_add_u64 v[4:5], v[4:5], 0, s[52:53]
	v_and_b32_e32 v6, 0x7ff, v3
	v_lshlrev_b32_e32 v22, 2, v6
	v_lshl_add_u64 v[6:7], s[20:21], 0, v[22:23]
	v_cmp_gt_i32_e32 vcc, s93, v3
	s_movk_i32 s9, 0x15ff
	s_mov_b64 s[52:53], 0x800
	v_cndmask_b32_e32 v7, v7, v5, vcc
	v_cndmask_b32_e32 v6, v6, v4, vcc
	global_load_dword v134, v[6:7], off
	v_add_u32_e32 v3, 0x200, v3
	v_lshl_add_u64 v[4:5], v[4:5], 0, s[52:53]
	v_and_b32_e32 v6, 0x7ff, v3
	v_lshlrev_b32_e32 v22, 2, v6
	v_lshl_add_u64 v[6:7], s[20:21], 0, v[22:23]
	v_cmp_gt_i32_e32 vcc, s93, v3
	s_movk_i32 s9, 0x15ff
	s_mov_b64 s[52:53], 0x800
	v_cndmask_b32_e32 v7, v7, v5, vcc
	v_cndmask_b32_e32 v6, v6, v4, vcc
	global_load_dword v135, v[6:7], off
	v_add_u32_e32 v3, 0x200, v3
	v_lshl_add_u64 v[4:5], v[4:5], 0, s[52:53]
	s_waitcnt vmcnt(11)
	v_mul_f32_e32 v8, 0xbfb8aa3b, v124
	v_exp_f32_e32 v8, v8
	s_nop 0
	v_add_f32_e32 v140, 1.0, v8
	v_rcp_f32_e32 v8, v140
	s_nop 0
	v_mul_f32_e32 v124, v124, v8
	ds_write_b32 v1, v124
	s_waitcnt vmcnt(10)
	v_mul_f32_e32 v8, 0xbfb8aa3b, v125
	v_exp_f32_e32 v8, v8
	s_nop 0
	v_add_f32_e32 v140, 1.0, v8
	v_rcp_f32_e32 v8, v140
	s_nop 0
	v_mul_f32_e32 v125, v125, v8
	ds_write_b32 v1, v125 offset:2048
	s_waitcnt vmcnt(9)
	v_mul_f32_e32 v8, 0xbfb8aa3b, v126
	v_exp_f32_e32 v8, v8
	s_nop 0
	v_add_f32_e32 v140, 1.0, v8
	v_rcp_f32_e32 v8, v140
	s_nop 0
	v_mul_f32_e32 v126, v126, v8
	ds_write_b32 v1, v126 offset:4096
	s_waitcnt vmcnt(8)
	v_mul_f32_e32 v8, 0xbfb8aa3b, v127
	v_exp_f32_e32 v8, v8
	s_nop 0
	v_add_f32_e32 v140, 1.0, v8
	v_rcp_f32_e32 v8, v140
	s_nop 0
	v_mul_f32_e32 v127, v127, v8
	ds_write_b32 v1, v127 offset:6144
	s_waitcnt vmcnt(7)
	v_mul_f32_e32 v8, 0xbfb8aa3b, v128
	v_exp_f32_e32 v8, v8
	s_nop 0
	v_add_f32_e32 v140, 1.0, v8
	v_rcp_f32_e32 v8, v140
	s_nop 0
	v_mul_f32_e32 v128, v128, v8
	ds_write_b32 v1, v128 offset:8192
	s_waitcnt vmcnt(6)
	v_mul_f32_e32 v8, 0xbfb8aa3b, v129
	v_exp_f32_e32 v8, v8
	s_nop 0
	v_add_f32_e32 v140, 1.0, v8
	v_rcp_f32_e32 v8, v140
	s_nop 0
	v_mul_f32_e32 v129, v129, v8
	ds_write_b32 v1, v129 offset:10240
	s_waitcnt vmcnt(5)
	v_mul_f32_e32 v8, 0xbfb8aa3b, v130
	v_exp_f32_e32 v8, v8
	s_nop 0
	v_add_f32_e32 v140, 1.0, v8
	v_rcp_f32_e32 v8, v140
	s_nop 0
	v_mul_f32_e32 v130, v130, v8
	ds_write_b32 v1, v130 offset:12288
	s_waitcnt vmcnt(4)
	v_mul_f32_e32 v8, 0xbfb8aa3b, v131
	v_exp_f32_e32 v8, v8
	s_nop 0
	v_add_f32_e32 v140, 1.0, v8
	v_rcp_f32_e32 v8, v140
	s_nop 0
	v_mul_f32_e32 v131, v131, v8
	ds_write_b32 v1, v131 offset:14336
	s_waitcnt vmcnt(3)
	v_mul_f32_e32 v8, 0xbfb8aa3b, v132
	v_exp_f32_e32 v8, v8
	s_nop 0
	v_add_f32_e32 v140, 1.0, v8
	v_rcp_f32_e32 v8, v140
	s_nop 0
	v_mul_f32_e32 v132, v132, v8
	ds_write_b32 v1, v132 offset:16384
	s_waitcnt vmcnt(2)
	v_mul_f32_e32 v8, 0xbfb8aa3b, v133
	v_exp_f32_e32 v8, v8
	s_nop 0
	v_add_f32_e32 v140, 1.0, v8
	v_rcp_f32_e32 v8, v140
	s_nop 0
	v_mul_f32_e32 v133, v133, v8
	ds_write_b32 v1, v133 offset:18432
	s_waitcnt vmcnt(1)
	v_mul_f32_e32 v8, 0xbfb8aa3b, v134
	v_exp_f32_e32 v8, v8
	s_nop 0
	v_add_f32_e32 v140, 1.0, v8
	v_rcp_f32_e32 v8, v140
	s_nop 0
	v_mul_f32_e32 v134, v134, v8
	ds_write_b32 v1, v134 offset:20480
	s_waitcnt vmcnt(0)
	v_mul_f32_e32 v8, 0xbfb8aa3b, v135
	v_exp_f32_e32 v8, v8
	s_nop 0
	v_add_f32_e32 v140, 1.0, v8
	v_rcp_f32_e32 v8, v140
	s_nop 0
	v_mul_f32_e32 v135, v135, v8
	ds_write_b32 v1, v135 offset:22528
	v_add_u32_e32 v1, 0x6000, v1

; __device__ __forceinline__ void mod_item(PREF P, int l, int nt, float* sm) {
;     ...
;     const int col = tid & 63, kg = tid >> 6; const float* w = P.w_ada + (size_t)l * DM * 6144 + nt * 64 + col;
;     float a0 = 0.f, a1 = 0.f, a2 = 0.f;
; #pragma unroll 16
;     for (int k = kg * 256; k < kg * 256 + 256; ++k) { const float wv = w[(size_t)k * 6144]; a0 += sc[k] * wv; a1 += sc[2048 + k] * wv; a2 += sc[4096 + k] * wv; }
.LBB0_100:
	v_lshlrev_b32_e32 v172, 2, v1
	s_nop 0
	v_readfirstlane_b32 s52, v4
	v_readfirstlane_b32 s53, v5
	s_nop 4
	global_load_dword v124, v172, s[52:53]
	s_add_u32 s52, s52, 0x6000
	s_addc_u32 s53, s53, 0
	global_load_dword v125, v172, s[52:53]
	s_add_u32 s52, s52, 0x6000
	s_addc_u32 s53, s53, 0
	global_load_dword v126, v172, s[52:53]
	s_add_u32 s52, s52, 0x6000
	s_addc_u32 s53, s53, 0
	global_load_dword v127, v172, s[52:53]
	s_add_u32 s52, s52, 0x6000
	s_addc_u32 s53, s53, 0
	global_load_dword v128, v172, s[52:53]
	s_add_u32 s52, s52, 0x6000
	s_addc_u32 s53, s53, 0
	global_load_dword v129, v172, s[52:53]
	s_add_u32 s52, s52, 0x6000
	s_addc_u32 s53, s53, 0
	global_load_dword v130, v172, s[52:53]
	s_add_u32 s52, s52, 0x6000
	s_addc_u32 s53, s53, 0
	global_load_dword v131, v172, s[52:53]
	s_add_u32 s52, s52, 0x6000
	s_addc_u32 s53, s53, 0
	global_load_dword v132, v172, s[52:53]
	s_add_u32 s52, s52, 0x6000
	s_addc_u32 s53, s53, 0
	global_load_dword v133, v172, s[52:53]
	s_add_u32 s52, s52, 0x6000
	s_addc_u32 s53, s53, 0
	global_load_dword v134, v172, s[52:53]
	s_add_u32 s52, s52, 0x6000
	s_addc_u32 s53, s53, 0
	global_load_dword v135, v172, s[52:53]
	s_add_u32 s52, s52, 0x6000
	s_addc_u32 s53, s53, 0
	global_load_dword v136, v172, s[52:53]
	s_add_u32 s52, s52, 0x6000
	s_addc_u32 s53, s53, 0
	global_load_dword v137, v172, s[52:53]
	s_add_u32 s52, s52, 0x6000
	s_addc_u32 s53, s53, 0
	global_load_dword v138, v172, s[52:53]
	s_add_u32 s52, s52, 0x6000
	s_addc_u32 s53, s53, 0
	global_load_dword v139, v172, s[52:53]
	s_add_u32 s52, s52, 0x6000
	s_addc_u32 s53, s53, 0
	global_load_dword v140, v172, s[52:53]
	s_add_u32 s52, s52, 0x6000
	s_addc_u32 s53, s53, 0
	global_load_dword v141, v172, s[52:53]
	s_add_u32 s52, s52, 0x6000
	s_addc_u32 s53, s53, 0
	global_load_dword v142, v172, s[52:53]
	s_add_u32 s52, s52, 0x6000
	s_addc_u32 s53, s53, 0
	global_load_dword v143, v172, s[52:53]
	s_add_u32 s52, s52, 0x6000
	s_addc_u32 s53, s53, 0
	global_load_dword v144, v172, s[52:53]
	s_add_u32 s52, s52, 0x6000
	s_addc_u32 s53, s53, 0
	global_load_dword v145, v172, s[52:53]
	s_add_u32 s52, s52, 0x6000
	s_addc_u32 s53, s53, 0
	global_load_dword v146, v172, s[52:53]
	s_add_u32 s52, s52, 0x6000
	s_addc_u32 s53, s53, 0
	global_load_dword v147, v172, s[52:53]
	s_add_u32 s52, s52, 0x6000
	s_addc_u32 s53, s53, 0
	global_load_dword v148, v172, s[52:53]
	s_add_u32 s52, s52, 0x6000
	s_addc_u32 s53, s53, 0
	global_load_dword v149, v172, s[52:53]
	s_add_u32 s52, s52, 0x6000
	s_addc_u32 s53, s53, 0
	global_load_dword v150, v172, s[52:53]
	s_add_u32 s52, s52, 0x6000
	s_addc_u32 s53, s53, 0
	global_load_dword v151, v172, s[52:53]
	s_add_u32 s52, s52, 0x6000
	s_addc_u32 s53, s53, 0
	global_load_dword v152, v172, s[52:53]
	s_add_u32 s52, s52, 0x6000
	s_addc_u32 s53, s53, 0
	global_load_dword v153, v172, s[52:53]
	s_add_u32 s52, s52, 0x6000
	s_addc_u32 s53, s53, 0
	global_load_dword v154, v172, s[52:53]
	s_add_u32 s52, s52, 0x6000
	s_addc_u32 s53, s53, 0
	global_load_dword v155, v172, s[52:53]
	s_add_u32 s52, s52, 0x6000
	s_addc_u32 s53, s53, 0
	global_load_dword v156, v172, s[52:53]
	s_add_u32 s52, s52, 0x6000
	s_addc_u32 s53, s53, 0
	global_load_dword v157, v172, s[52:53]
	s_add_u32 s52, s52, 0x6000
	s_addc_u32 s53, s53, 0
	global_load_dword v158, v172, s[52:53]
	s_add_u32 s52, s52, 0x6000
	s_addc_u32 s53, s53, 0
	global_load_dword v159, v172, s[52:53]
	s_add_u32 s52, s52, 0x6000
	s_addc_u32 s53, s53, 0
	global_load_dword v160, v172, s[52:53]
	s_add_u32 s52, s52, 0x6000
	s_addc_u32 s53, s53, 0
	global_load_dword v161, v172, s[52:53]
	s_add_u32 s52, s52, 0x6000
	s_addc_u32 s53, s53, 0
	global_load_dword v162, v172, s[52:53]
	s_add_u32 s52, s52, 0x6000
	s_addc_u32 s53, s53, 0
	global_load_dword v163, v172, s[52:53]
	s_add_u32 s52, s52, 0x6000
	s_addc_u32 s53, s53, 0
	global_load_dword v164, v172, s[52:53]
	s_add_u32 s52, s52, 0x6000
	s_addc_u32 s53, s53, 0
	global_load_dword v165, v172, s[52:53]
	s_add_u32 s52, s52, 0x6000
	s_addc_u32 s53, s53, 0
	global_load_dword v166, v172, s[52:53]
	s_add_u32 s52, s52, 0x6000
	s_addc_u32 s53, s53, 0
	global_load_dword v167, v172, s[52:53]
	s_add_u32 s52, s52, 0x6000
	s_addc_u32 s53, s53, 0
	global_load_dword v168, v172, s[52:53]
	s_add_u32 s52, s52, 0x6000
	s_addc_u32 s53, s53, 0
	global_load_dword v169, v172, s[52:53]
	s_add_u32 s52, s52, 0x6000
	s_addc_u32 s53, s53, 0
	global_load_dword v170, v172, s[52:53]
	s_add_u32 s52, s52, 0x6000
	s_addc_u32 s53, s53, 0
	global_load_dword v171, v172, s[52:53]
	s_add_u32 s52, s52, 0x6000
	s_addc_u32 s53, s53, 0
	ds_read_b128 v[174:177], v12
	ds_read_b128 v[178:181], v12 offset:8192
	ds_read_b128 v[182:185], v12 offset:16384
	ds_read_b128 v[186:189], v12 offset:16
	ds_read_b128 v[190:193], v12 offset:8208
	ds_read_b128 v[194:197], v12 offset:16400
	ds_read_b128 v[198:201], v12 offset:32
	ds_read_b128 v[202:205], v12 offset:8224
	ds_read_b128 v[206:209], v12 offset:16416
	ds_read_b128 v[210:213], v12 offset:48
	ds_read_b128 v[214:217], v12 offset:8240
	ds_read_b128 v[218:221], v12 offset:16432
	s_waitcnt vmcnt(47) lgkmcnt(9)
	v_fmac_f32_e32 v6, v124, v174
	v_fmac_f32_e32 v7, v124, v178
	v_fmac_f32_e32 v11, v124, v182
	global_load_dword v124, v172, s[52:53]
	s_add_u32 s52, s52, 0x6000
	s_addc_u32 s53, s53, 0
	s_waitcnt vmcnt(47)
	v_fmac_f32_e32 v6, v125, v175
	v_fmac_f32_e32 v7, v125, v179
	v_fmac_f32_e32 v11, v125, v183
	global_load_dword v125, v172, s[52:53]
	s_add_u32 s52, s52, 0x6000
	s_addc_u32 s53, s53, 0
	s_waitcnt vmcnt(47)
	v_fmac_f32_e32 v6, v126, v176
	v_fmac_f32_e32 v7, v126, v180
	v_fmac_f32_e32 v11, v126, v184
	global_load_dword v126, v172, s[52:53]
	s_add_u32 s52, s52, 0x6000
	s_addc_u32 s53, s53, 0
	s_waitcnt vmcnt(47)
; __device__ __forceinline__ void mod_item(PREF P, int l, int nt, float* sm) {
;     ...
;     const int col = tid & 63, kg = tid >> 6; const float* w = P.w_ada + (size_t)l * DM * 6144 + nt * 64 + col;
;     float a0 = 0.f, a1 = 0.f, a2 = 0.f;
; #pragma unroll 16
;     for (int k = kg * 256; k < kg * 256 + 256; ++k) { const float wv = w[(size_t)k * 6144]; a0 += sc[k] * wv; a1 += sc[2048 + k] * wv; a2 += sc[4096 + k] * wv; }
	v_fmac_f32_e32 v6, v127, v177
	v_fmac_f32_e32 v7, v127, v181
	v_fmac_f32_e32 v11, v127, v185
	global_load_dword v127, v172, s[52:53]
	s_add_u32 s52, s52, 0x6000
	s_addc_u32 s53, s53, 0
	ds_read_b128 v[174:177], v12 offset:64
	ds_read_b128 v[178:181], v12 offset:8256
	ds_read_b128 v[182:185], v12 offset:16448
	s_waitcnt vmcnt(47) lgkmcnt(9)
	v_fmac_f32_e32 v6, v128, v186
	v_fmac_f32_e32 v7, v128, v190
	v_fmac_f32_e32 v11, v128, v194
	global_load_dword v128, v172, s[52:53]
	s_add_u32 s52, s52, 0x6000
	s_addc_u32 s53, s53, 0
	s_waitcnt vmcnt(47)
	v_fmac_f32_e32 v6, v129, v187
	v_fmac_f32_e32 v7, v129, v191
	v_fmac_f32_e32 v11, v129, v195
	global_load_dword v129, v172, s[52:53]
	s_add_u32 s52, s52, 0x6000
	s_addc_u32 s53, s53, 0
	s_waitcnt vmcnt(47)
	v_fmac_f32_e32 v6, v130, v188
	v_fmac_f32_e32 v7, v130, v192
	v_fmac_f32_e32 v11, v130, v196
	global_load_dword v130, v172, s[52:53]
	s_add_u32 s52, s52, 0x6000
	s_addc_u32 s53, s53, 0
	s_waitcnt vmcnt(47)
	v_fmac_f32_e32 v6, v131, v189
	v_fmac_f32_e32 v7, v131, v193
	v_fmac_f32_e32 v11, v131, v197
	global_load_dword v131, v172, s[52:53]
	s_add_u32 s52, s52, 0x6000
	s_addc_u32 s53, s53, 0
	ds_read_b128 v[186:189], v12 offset:80
	ds_read_b128 v[190:193], v12 offset:8272
	ds_read_b128 v[194:197], v12 offset:16464
	s_waitcnt vmcnt(47) lgkmcnt(9)
	v_fmac_f32_e32 v6, v132, v198
	v_fmac_f32_e32 v7, v132, v202
	v_fmac_f32_e32 v11, v132, v206
	global_load_dword v132, v172, s[52:53]
	s_add_u32 s52, s52, 0x6000
	s_addc_u32 s53, s53, 0
	s_waitcnt vmcnt(47)
	v_fmac_f32_e32 v6, v133, v199
	v_fmac_f32_e32 v7, v133, v203
	v_fmac_f32_e32 v11, v133, v207
	global_load_dword v133, v172, s[52:53]
	s_add_u32 s52, s52, 0x6000
	s_addc_u32 s53, s53, 0
	s_waitcnt vmcnt(47)
	v_fmac_f32_e32 v6, v134, v200
	v_fmac_f32_e32 v7, v134, v204
	v_fmac_f32_e32 v11, v134, v208
	global_load_dword v134, v172, s[52:53]
	s_add_u32 s52, s52, 0x6000
	s_addc_u32 s53, s53, 0
	s_waitcnt vmcnt(47)
	v_fmac_f32_e32 v6, v135, v201
	v_fmac_f32_e32 v7, v135, v205
	v_fmac_f32_e32 v11, v135, v209
	global_load_dword v135, v172, s[52:53]
	s_add_u32 s52, s52, 0x6000
	s_addc_u32 s53, s53, 0
	ds_read_b128 v[198:201], v12 offset:96
	ds_read_b128 v[202:205], v12 offset:8288
	ds_read_b128 v[206:209], v12 offset:16480
	s_waitcnt vmcnt(47) lgkmcnt(9)
	v_fmac_f32_e32 v6, v136, v210
	v_fmac_f32_e32 v7, v136, v214
	v_fmac_f32_e32 v11, v136, v218
	global_load_dword v136, v172, s[52:53]
	s_add_u32 s52, s52, 0x6000
	s_addc_u32 s53, s53, 0
	s_waitcnt vmcnt(47)
	v_fmac_f32_e32 v6, v137, v211
	v_fmac_f32_e32 v7, v137, v215
	v_fmac_f32_e32 v11, v137, v219
	global_load_dword v137, v172, s[52:53]
	s_add_u32 s52, s52, 0x6000
	s_addc_u32 s53, s53, 0
	s_waitcnt vmcnt(47)
	v_fmac_f32_e32 v6, v138, v212
	v_fmac_f32_e32 v7, v138, v216
	v_fmac_f32_e32 v11, v138, v220
	global_load_dword v138, v172, s[52:53]
	s_add_u32 s52, s52, 0x6000
	s_addc_u32 s53, s53, 0
	s_waitcnt vmcnt(47)
	v_fmac_f32_e32 v6, v139, v213
	v_fmac_f32_e32 v7, v139, v217
	v_fmac_f32_e32 v11, v139, v221
	global_load_dword v139, v172, s[52:53]
	s_add_u32 s52, s52, 0x6000
	s_addc_u32 s53, s53, 0
	ds_read_b128 v[210:213], v12 offset:112
	ds_read_b128 v[214:217], v12 offset:8304
	ds_read_b128 v[218:221], v12 offset:16496
	s_waitcnt vmcnt(47) lgkmcnt(9)
	v_fmac_f32_e32 v6, v140, v174
	v_fmac_f32_e32 v7, v140, v178
	v_fmac_f32_e32 v11, v140, v182
	global_load_dword v140, v172, s[52:53]
	s_add_u32 s52, s52, 0x6000
	s_addc_u32 s53, s53, 0
	s_waitcnt vmcnt(47)
	v_fmac_f32_e32 v6, v141, v175
	v_fmac_f32_e32 v7, v141, v179
	v_fmac_f32_e32 v11, v141, v183
	global_load_dword v141, v172, s[52:53]
	s_add_u32 s52, s52, 0x6000
	s_addc_u32 s53, s53, 0
	s_waitcnt vmcnt(47)
	v_fmac_f32_e32 v6, v142, v176
	v_fmac_f32_e32 v7, v142, v180
	v_fmac_f32_e32 v11, v142, v184
	global_load_dword v142, v172, s[52:53]
	s_add_u32 s52, s52, 0x6000
	s_addc_u32 s53, s53, 0
	s_waitcnt vmcnt(47)
	v_fmac_f32_e32 v6, v143, v177
	v_fmac_f32_e32 v7, v143, v181
	v_fmac_f32_e32 v11, v143, v185
	global_load_dword v143, v172, s[52:53]
	s_add_u32 s52, s52, 0x6000
	s_addc_u32 s53, s53, 0
	ds_read_b128 v[174:177], v12 offset:128
	ds_read_b128 v[178:181], v12 offset:8320
	ds_read_b128 v[182:185], v12 offset:16512
	s_waitcnt vmcnt(47) lgkmcnt(9)
	v_fmac_f32_e32 v6, v144, v186
	v_fmac_f32_e32 v7, v144, v190
	v_fmac_f32_e32 v11, v144, v194
	global_load_dword v144, v172, s[52:53]
	s_add_u32 s52, s52, 0x6000
	s_addc_u32 s53, s53, 0
	s_waitcnt vmcnt(47)
	v_fmac_f32_e32 v6, v145, v187
	v_fmac_f32_e32 v7, v145, v191
	v_fmac_f32_e32 v11, v145, v195
	global_load_dword v145, v172, s[52:53]
	s_add_u32 s52, s52, 0x6000
	s_addc_u32 s53, s53, 0
	s_waitcnt vmcnt(47)
	v_fmac_f32_e32 v6, v146, v188
	v_fmac_f32_e32 v7, v146, v192
	v_fmac_f32_e32 v11, v146, v196
	global_load_dword v146, v172, s[52:53]
	s_add_u32 s52, s52, 0x6000
	s_addc_u32 s53, s53, 0
	s_waitcnt vmcnt(47)
	v_fmac_f32_e32 v6, v147, v189
	v_fmac_f32_e32 v7, v147, v193
	v_fmac_f32_e32 v11, v147, v197
	global_load_dword v147, v172, s[52:53]
	s_add_u32 s52, s52, 0x6000
	s_addc_u32 s53, s53, 0
	ds_read_b128 v[186:189], v12 offset:144
	ds_read_b128 v[190:193], v12 offset:8336
	ds_read_b128 v[194:197], v12 offset:16528
	s_waitcnt vmcnt(47) lgkmcnt(9)
	v_fmac_f32_e32 v6, v148, v198
	v_fmac_f32_e32 v7, v148, v202
	v_fmac_f32_e32 v11, v148, v206
	global_load_dword v148, v172, s[52:53]
	s_add_u32 s52, s52, 0x6000
	s_addc_u32 s53, s53, 0
	s_waitcnt vmcnt(47)
	v_fmac_f32_e32 v6, v149, v199
	v_fmac_f32_e32 v7, v149, v203
	v_fmac_f32_e32 v11, v149, v207
	global_load_dword v149, v172, s[52:53]
	s_add_u32 s52, s52, 0x6000
	s_addc_u32 s53, s53, 0
	s_waitcnt vmcnt(47)
; __device__ __forceinline__ void mod_item(PREF P, int l, int nt, float* sm) {
;     ...
;     const int col = tid & 63, kg = tid >> 6; const float* w = P.w_ada + (size_t)l * DM * 6144 + nt * 64 + col;
;     float a0 = 0.f, a1 = 0.f, a2 = 0.f;
; #pragma unroll 16
;     for (int k = kg * 256; k < kg * 256 + 256; ++k) { const float wv = w[(size_t)k * 6144]; a0 += sc[k] * wv; a1 += sc[2048 + k] * wv; a2 += sc[4096 + k] * wv; }
	v_fmac_f32_e32 v6, v150, v200
	v_fmac_f32_e32 v7, v150, v204
	v_fmac_f32_e32 v11, v150, v208
	global_load_dword v150, v172, s[52:53]
	s_add_u32 s52, s52, 0x6000
	s_addc_u32 s53, s53, 0
	s_waitcnt vmcnt(47)
	v_fmac_f32_e32 v6, v151, v201
	v_fmac_f32_e32 v7, v151, v205
	v_fmac_f32_e32 v11, v151, v209
	global_load_dword v151, v172, s[52:53]
	s_add_u32 s52, s52, 0x6000
	s_addc_u32 s53, s53, 0
	ds_read_b128 v[198:201], v12 offset:160
	ds_read_b128 v[202:205], v12 offset:8352
	ds_read_b128 v[206:209], v12 offset:16544
	s_waitcnt vmcnt(47) lgkmcnt(9)
	v_fmac_f32_e32 v6, v152, v210
	v_fmac_f32_e32 v7, v152, v214
	v_fmac_f32_e32 v11, v152, v218
	global_load_dword v152, v172, s[52:53]
	s_add_u32 s52, s52, 0x6000
	s_addc_u32 s53, s53, 0
	s_waitcnt vmcnt(47)
	v_fmac_f32_e32 v6, v153, v211
	v_fmac_f32_e32 v7, v153, v215
	v_fmac_f32_e32 v11, v153, v219
	global_load_dword v153, v172, s[52:53]
	s_add_u32 s52, s52, 0x6000
	s_addc_u32 s53, s53, 0
	s_waitcnt vmcnt(47)
	v_fmac_f32_e32 v6, v154, v212
	v_fmac_f32_e32 v7, v154, v216
	v_fmac_f32_e32 v11, v154, v220
	global_load_dword v154, v172, s[52:53]
	s_add_u32 s52, s52, 0x6000
	s_addc_u32 s53, s53, 0
	s_waitcnt vmcnt(47)
	v_fmac_f32_e32 v6, v155, v213
	v_fmac_f32_e32 v7, v155, v217
	v_fmac_f32_e32 v11, v155, v221
	global_load_dword v155, v172, s[52:53]
	s_add_u32 s52, s52, 0x6000
	s_addc_u32 s53, s53, 0
	ds_read_b128 v[210:213], v12 offset:176
	ds_read_b128 v[214:217], v12 offset:8368
	ds_read_b128 v[218:221], v12 offset:16560
	s_waitcnt vmcnt(47) lgkmcnt(9)
	v_fmac_f32_e32 v6, v156, v174
	v_fmac_f32_e32 v7, v156, v178
	v_fmac_f32_e32 v11, v156, v182
	global_load_dword v156, v172, s[52:53]
	s_add_u32 s52, s52, 0x6000
	s_addc_u32 s53, s53, 0
	s_waitcnt vmcnt(47)
	v_fmac_f32_e32 v6, v157, v175
	v_fmac_f32_e32 v7, v157, v179
	v_fmac_f32_e32 v11, v157, v183
	global_load_dword v157, v172, s[52:53]
	s_add_u32 s52, s52, 0x6000
	s_addc_u32 s53, s53, 0
	s_waitcnt vmcnt(47)
	v_fmac_f32_e32 v6, v158, v176
	v_fmac_f32_e32 v7, v158, v180
	v_fmac_f32_e32 v11, v158, v184
	global_load_dword v158, v172, s[52:53]
	s_add_u32 s52, s52, 0x6000
	s_addc_u32 s53, s53, 0
	s_waitcnt vmcnt(47)
	v_fmac_f32_e32 v6, v159, v177
	v_fmac_f32_e32 v7, v159, v181
	v_fmac_f32_e32 v11, v159, v185
	global_load_dword v159, v172, s[52:53]
	s_add_u32 s52, s52, 0x6000
	s_addc_u32 s53, s53, 0
	ds_read_b128 v[174:177], v12 offset:192
	ds_read_b128 v[178:181], v12 offset:8384
	ds_read_b128 v[182:185], v12 offset:16576
	s_waitcnt vmcnt(47) lgkmcnt(9)
	v_fmac_f32_e32 v6, v160, v186
	v_fmac_f32_e32 v7, v160, v190
	v_fmac_f32_e32 v11, v160, v194
	global_load_dword v160, v172, s[52:53]
	s_add_u32 s52, s52, 0x6000
	s_addc_u32 s53, s53, 0
	s_waitcnt vmcnt(47)
	v_fmac_f32_e32 v6, v161, v187
	v_fmac_f32_e32 v7, v161, v191
	v_fmac_f32_e32 v11, v161, v195
	global_load_dword v161, v172, s[52:53]
	s_add_u32 s52, s52, 0x6000
	s_addc_u32 s53, s53, 0
	s_waitcnt vmcnt(47)
	v_fmac_f32_e32 v6, v162, v188
	v_fmac_f32_e32 v7, v162, v192
	v_fmac_f32_e32 v11, v162, v196
	global_load_dword v162, v172, s[52:53]
	s_add_u32 s52, s52, 0x6000
	s_addc_u32 s53, s53, 0
	s_waitcnt vmcnt(47)
	v_fmac_f32_e32 v6, v163, v189
	v_fmac_f32_e32 v7, v163, v193
	v_fmac_f32_e32 v11, v163, v197
	global_load_dword v163, v172, s[52:53]
	s_add_u32 s52, s52, 0x6000
	s_addc_u32 s53, s53, 0
	ds_read_b128 v[186:189], v12 offset:208
	ds_read_b128 v[190:193], v12 offset:8400
	ds_read_b128 v[194:197], v12 offset:16592
	s_waitcnt vmcnt(47) lgkmcnt(9)
	v_fmac_f32_e32 v6, v164, v198
	v_fmac_f32_e32 v7, v164, v202
	v_fmac_f32_e32 v11, v164, v206
	global_load_dword v164, v172, s[52:53]
	s_add_u32 s52, s52, 0x6000
	s_addc_u32 s53, s53, 0
	s_waitcnt vmcnt(47)
	v_fmac_f32_e32 v6, v165, v199
	v_fmac_f32_e32 v7, v165, v203
	v_fmac_f32_e32 v11, v165, v207
	global_load_dword v165, v172, s[52:53]
	s_add_u32 s52, s52, 0x6000
	s_addc_u32 s53, s53, 0
	s_waitcnt vmcnt(47)
	v_fmac_f32_e32 v6, v166, v200
	v_fmac_f32_e32 v7, v166, v204
	v_fmac_f32_e32 v11, v166, v208
	global_load_dword v166, v172, s[52:53]
	s_add_u32 s52, s52, 0x6000
	s_addc_u32 s53, s53, 0
	s_waitcnt vmcnt(47)
	v_fmac_f32_e32 v6, v167, v201
	v_fmac_f32_e32 v7, v167, v205
	v_fmac_f32_e32 v11, v167, v209
	global_load_dword v167, v172, s[52:53]
	s_add_u32 s52, s52, 0x6000
	s_addc_u32 s53, s53, 0
	ds_read_b128 v[198:201], v12 offset:224
	ds_read_b128 v[202:205], v12 offset:8416
	ds_read_b128 v[206:209], v12 offset:16608
	s_waitcnt vmcnt(47) lgkmcnt(9)
	v_fmac_f32_e32 v6, v168, v210
	v_fmac_f32_e32 v7, v168, v214
	v_fmac_f32_e32 v11, v168, v218
	global_load_dword v168, v172, s[52:53]
	s_add_u32 s52, s52, 0x6000
	s_addc_u32 s53, s53, 0
	s_waitcnt vmcnt(47)
	v_fmac_f32_e32 v6, v169, v211
	v_fmac_f32_e32 v7, v169, v215
	v_fmac_f32_e32 v11, v169, v219
	global_load_dword v169, v172, s[52:53]
	s_add_u32 s52, s52, 0x6000
	s_addc_u32 s53, s53, 0
	s_waitcnt vmcnt(47)
	v_fmac_f32_e32 v6, v170, v212
	v_fmac_f32_e32 v7, v170, v216
	v_fmac_f32_e32 v11, v170, v220
	global_load_dword v170, v172, s[52:53]
	s_add_u32 s52, s52, 0x6000
	s_addc_u32 s53, s53, 0
	s_waitcnt vmcnt(47)
	v_fmac_f32_e32 v6, v171, v213
	v_fmac_f32_e32 v7, v171, v217
	v_fmac_f32_e32 v11, v171, v221
	global_load_dword v171, v172, s[52:53]
	s_add_u32 s52, s52, 0x6000
	s_addc_u32 s53, s53, 0
	ds_read_b128 v[210:213], v12 offset:240
	ds_read_b128 v[214:217], v12 offset:8432
	ds_read_b128 v[218:221], v12 offset:16624
	s_waitcnt vmcnt(47) lgkmcnt(9)
	v_fmac_f32_e32 v6, v124, v174
	v_fmac_f32_e32 v7, v124, v178
	v_fmac_f32_e32 v11, v124, v182
	global_load_dword v124, v172, s[52:53]
	s_add_u32 s52, s52, 0x6000
	s_addc_u32 s53, s53, 0
	s_waitcnt vmcnt(47)
; __device__ __forceinline__ void mod_item(PREF P, int l, int nt, float* sm) {
;     ...
;     const int col = tid & 63, kg = tid >> 6; const float* w = P.w_ada + (size_t)l * DM * 6144 + nt * 64 + col;
;     float a0 = 0.f, a1 = 0.f, a2 = 0.f;
; #pragma unroll 16
;     for (int k = kg * 256; k < kg * 256 + 256; ++k) { const float wv = w[(size_t)k * 6144]; a0 += sc[k] * wv; a1 += sc[2048 + k] * wv; a2 += sc[4096 + k] * wv; }
	v_fmac_f32_e32 v6, v125, v175
	v_fmac_f32_e32 v7, v125, v179
	v_fmac_f32_e32 v11, v125, v183
	global_load_dword v125, v172, s[52:53]
	s_add_u32 s52, s52, 0x6000
	s_addc_u32 s53, s53, 0
	s_waitcnt vmcnt(47)
	v_fmac_f32_e32 v6, v126, v176
	v_fmac_f32_e32 v7, v126, v180
	v_fmac_f32_e32 v11, v126, v184
	global_load_dword v126, v172, s[52:53]
	s_add_u32 s52, s52, 0x6000
	s_addc_u32 s53, s53, 0
	s_waitcnt vmcnt(47)
	v_fmac_f32_e32 v6, v127, v177
	v_fmac_f32_e32 v7, v127, v181
	v_fmac_f32_e32 v11, v127, v185
	global_load_dword v127, v172, s[52:53]
	s_add_u32 s52, s52, 0x6000
	s_addc_u32 s53, s53, 0
	ds_read_b128 v[174:177], v12 offset:256
	ds_read_b128 v[178:181], v12 offset:8448
	ds_read_b128 v[182:185], v12 offset:16640
	s_waitcnt vmcnt(47) lgkmcnt(9)
	v_fmac_f32_e32 v6, v128, v186
	v_fmac_f32_e32 v7, v128, v190
	v_fmac_f32_e32 v11, v128, v194
	global_load_dword v128, v172, s[52:53]
	s_add_u32 s52, s52, 0x6000
	s_addc_u32 s53, s53, 0
	s_waitcnt vmcnt(47)
	v_fmac_f32_e32 v6, v129, v187
	v_fmac_f32_e32 v7, v129, v191
	v_fmac_f32_e32 v11, v129, v195
	global_load_dword v129, v172, s[52:53]
	s_add_u32 s52, s52, 0x6000
	s_addc_u32 s53, s53, 0
	s_waitcnt vmcnt(47)
	v_fmac_f32_e32 v6, v130, v188
	v_fmac_f32_e32 v7, v130, v192
	v_fmac_f32_e32 v11, v130, v196
	global_load_dword v130, v172, s[52:53]
	s_add_u32 s52, s52, 0x6000
	s_addc_u32 s53, s53, 0
	s_waitcnt vmcnt(47)
	v_fmac_f32_e32 v6, v131, v189
	v_fmac_f32_e32 v7, v131, v193
	v_fmac_f32_e32 v11, v131, v197
	global_load_dword v131, v172, s[52:53]
	s_add_u32 s52, s52, 0x6000
	s_addc_u32 s53, s53, 0
	ds_read_b128 v[186:189], v12 offset:272
	ds_read_b128 v[190:193], v12 offset:8464
	ds_read_b128 v[194:197], v12 offset:16656
	s_waitcnt vmcnt(47) lgkmcnt(9)
	v_fmac_f32_e32 v6, v132, v198
	v_fmac_f32_e32 v7, v132, v202
	v_fmac_f32_e32 v11, v132, v206
	global_load_dword v132, v172, s[52:53]
	s_add_u32 s52, s52, 0x6000
	s_addc_u32 s53, s53, 0
	s_waitcnt vmcnt(47)
	v_fmac_f32_e32 v6, v133, v199
	v_fmac_f32_e32 v7, v133, v203
	v_fmac_f32_e32 v11, v133, v207
	global_load_dword v133, v172, s[52:53]
	s_add_u32 s52, s52, 0x6000
	s_addc_u32 s53, s53, 0
	s_waitcnt vmcnt(47)
	v_fmac_f32_e32 v6, v134, v200
	v_fmac_f32_e32 v7, v134, v204
	v_fmac_f32_e32 v11, v134, v208
	global_load_dword v134, v172, s[52:53]
	s_add_u32 s52, s52, 0x6000
	s_addc_u32 s53, s53, 0
	s_waitcnt vmcnt(47)
	v_fmac_f32_e32 v6, v135, v201
	v_fmac_f32_e32 v7, v135, v205
	v_fmac_f32_e32 v11, v135, v209
	global_load_dword v135, v172, s[52:53]
	s_add_u32 s52, s52, 0x6000
	s_addc_u32 s53, s53, 0
	ds_read_b128 v[198:201], v12 offset:288
	ds_read_b128 v[202:205], v12 offset:8480
	ds_read_b128 v[206:209], v12 offset:16672
	s_waitcnt vmcnt(47) lgkmcnt(9)
	v_fmac_f32_e32 v6, v136, v210
	v_fmac_f32_e32 v7, v136, v214
	v_fmac_f32_e32 v11, v136, v218
	global_load_dword v136, v172, s[52:53]
	s_add_u32 s52, s52, 0x6000
	s_addc_u32 s53, s53, 0
	s_waitcnt vmcnt(47)
	v_fmac_f32_e32 v6, v137, v211
	v_fmac_f32_e32 v7, v137, v215
	v_fmac_f32_e32 v11, v137, v219
	global_load_dword v137, v172, s[52:53]
	s_add_u32 s52, s52, 0x6000
	s_addc_u32 s53, s53, 0
	s_waitcnt vmcnt(47)
	v_fmac_f32_e32 v6, v138, v212
	v_fmac_f32_e32 v7, v138, v216
	v_fmac_f32_e32 v11, v138, v220
	global_load_dword v138, v172, s[52:53]
	s_add_u32 s52, s52, 0x6000
	s_addc_u32 s53, s53, 0
	s_waitcnt vmcnt(47)
	v_fmac_f32_e32 v6, v139, v213
	v_fmac_f32_e32 v7, v139, v217
	v_fmac_f32_e32 v11, v139, v221
	global_load_dword v139, v172, s[52:53]
	s_add_u32 s52, s52, 0x6000
	s_addc_u32 s53, s53, 0
	ds_read_b128 v[210:213], v12 offset:304
	ds_read_b128 v[214:217], v12 offset:8496
	ds_read_b128 v[218:221], v12 offset:16688
	s_waitcnt vmcnt(47) lgkmcnt(9)
	v_fmac_f32_e32 v6, v140, v174
	v_fmac_f32_e32 v7, v140, v178
	v_fmac_f32_e32 v11, v140, v182
	global_load_dword v140, v172, s[52:53]
	s_add_u32 s52, s52, 0x6000
	s_addc_u32 s53, s53, 0
	s_waitcnt vmcnt(47)
	v_fmac_f32_e32 v6, v141, v175
	v_fmac_f32_e32 v7, v141, v179
	v_fmac_f32_e32 v11, v141, v183
	global_load_dword v141, v172, s[52:53]
	s_add_u32 s52, s52, 0x6000
	s_addc_u32 s53, s53, 0
	s_waitcnt vmcnt(47)
	v_fmac_f32_e32 v6, v142, v176
	v_fmac_f32_e32 v7, v142, v180
	v_fmac_f32_e32 v11, v142, v184
	global_load_dword v142, v172, s[52:53]
	s_add_u32 s52, s52, 0x6000
	s_addc_u32 s53, s53, 0
	s_waitcnt vmcnt(47)
	v_fmac_f32_e32 v6, v143, v177
	v_fmac_f32_e32 v7, v143, v181
	v_fmac_f32_e32 v11, v143, v185
	global_load_dword v143, v172, s[52:53]
	s_add_u32 s52, s52, 0x6000
	s_addc_u32 s53, s53, 0
	ds_read_b128 v[174:177], v12 offset:320
	ds_read_b128 v[178:181], v12 offset:8512
	ds_read_b128 v[182:185], v12 offset:16704
	s_waitcnt vmcnt(47) lgkmcnt(9)
	v_fmac_f32_e32 v6, v144, v186
	v_fmac_f32_e32 v7, v144, v190
	v_fmac_f32_e32 v11, v144, v194
	global_load_dword v144, v172, s[52:53]
	s_add_u32 s52, s52, 0x6000
	s_addc_u32 s53, s53, 0
	s_waitcnt vmcnt(47)
	v_fmac_f32_e32 v6, v145, v187
	v_fmac_f32_e32 v7, v145, v191
	v_fmac_f32_e32 v11, v145, v195
	global_load_dword v145, v172, s[52:53]
	s_add_u32 s52, s52, 0x6000
	s_addc_u32 s53, s53, 0
	s_waitcnt vmcnt(47)
	v_fmac_f32_e32 v6, v146, v188
	v_fmac_f32_e32 v7, v146, v192
	v_fmac_f32_e32 v11, v146, v196
	global_load_dword v146, v172, s[52:53]
	s_add_u32 s52, s52, 0x6000
	s_addc_u32 s53, s53, 0
	s_waitcnt vmcnt(47)
	v_fmac_f32_e32 v6, v147, v189
	v_fmac_f32_e32 v7, v147, v193
	v_fmac_f32_e32 v11, v147, v197
	global_load_dword v147, v172, s[52:53]
	s_add_u32 s52, s52, 0x6000
	s_addc_u32 s53, s53, 0
	ds_read_b128 v[186:189], v12 offset:336
	ds_read_b128 v[190:193], v12 offset:8528
	ds_read_b128 v[194:197], v12 offset:16720
	s_waitcnt vmcnt(47) lgkmcnt(9)
; __device__ __forceinline__ void mod_item(PREF P, int l, int nt, float* sm) {
;     ...
;     const int col = tid & 63, kg = tid >> 6; const float* w = P.w_ada + (size_t)l * DM * 6144 + nt * 64 + col;
;     float a0 = 0.f, a1 = 0.f, a2 = 0.f;
; #pragma unroll 16
;     for (int k = kg * 256; k < kg * 256 + 256; ++k) { const float wv = w[(size_t)k * 6144]; a0 += sc[k] * wv; a1 += sc[2048 + k] * wv; a2 += sc[4096 + k] * wv; }
	v_fmac_f32_e32 v6, v148, v198
	v_fmac_f32_e32 v7, v148, v202
	v_fmac_f32_e32 v11, v148, v206
	global_load_dword v148, v172, s[52:53]
	s_add_u32 s52, s52, 0x6000
	s_addc_u32 s53, s53, 0
	s_waitcnt vmcnt(47)
	v_fmac_f32_e32 v6, v149, v199
	v_fmac_f32_e32 v7, v149, v203
	v_fmac_f32_e32 v11, v149, v207
	global_load_dword v149, v172, s[52:53]
	s_add_u32 s52, s52, 0x6000
	s_addc_u32 s53, s53, 0
	s_waitcnt vmcnt(47)
	v_fmac_f32_e32 v6, v150, v200
	v_fmac_f32_e32 v7, v150, v204
	v_fmac_f32_e32 v11, v150, v208
	global_load_dword v150, v172, s[52:53]
	s_add_u32 s52, s52, 0x6000
	s_addc_u32 s53, s53, 0
	s_waitcnt vmcnt(47)
	v_fmac_f32_e32 v6, v151, v201
	v_fmac_f32_e32 v7, v151, v205
	v_fmac_f32_e32 v11, v151, v209
	global_load_dword v151, v172, s[52:53]
	s_add_u32 s52, s52, 0x6000
	s_addc_u32 s53, s53, 0
	ds_read_b128 v[198:201], v12 offset:352
	ds_read_b128 v[202:205], v12 offset:8544
	ds_read_b128 v[206:209], v12 offset:16736
	s_waitcnt vmcnt(47) lgkmcnt(9)
	v_fmac_f32_e32 v6, v152, v210
	v_fmac_f32_e32 v7, v152, v214
	v_fmac_f32_e32 v11, v152, v218
	global_load_dword v152, v172, s[52:53]
	s_add_u32 s52, s52, 0x6000
	s_addc_u32 s53, s53, 0
	s_waitcnt vmcnt(47)
	v_fmac_f32_e32 v6, v153, v211
	v_fmac_f32_e32 v7, v153, v215
	v_fmac_f32_e32 v11, v153, v219
	global_load_dword v153, v172, s[52:53]
	s_add_u32 s52, s52, 0x6000
	s_addc_u32 s53, s53, 0
	s_waitcnt vmcnt(47)
	v_fmac_f32_e32 v6, v154, v212
	v_fmac_f32_e32 v7, v154, v216
	v_fmac_f32_e32 v11, v154, v220
	global_load_dword v154, v172, s[52:53]
	s_add_u32 s52, s52, 0x6000
	s_addc_u32 s53, s53, 0
	s_waitcnt vmcnt(47)
	v_fmac_f32_e32 v6, v155, v213
	v_fmac_f32_e32 v7, v155, v217
	v_fmac_f32_e32 v11, v155, v221
	global_load_dword v155, v172, s[52:53]
	s_add_u32 s52, s52, 0x6000
	s_addc_u32 s53, s53, 0
	ds_read_b128 v[210:213], v12 offset:368
	ds_read_b128 v[214:217], v12 offset:8560
	ds_read_b128 v[218:221], v12 offset:16752
	s_waitcnt vmcnt(47) lgkmcnt(9)
	v_fmac_f32_e32 v6, v156, v174
	v_fmac_f32_e32 v7, v156, v178
	v_fmac_f32_e32 v11, v156, v182
	global_load_dword v156, v172, s[52:53]
	s_add_u32 s52, s52, 0x6000
	s_addc_u32 s53, s53, 0
	s_waitcnt vmcnt(47)
	v_fmac_f32_e32 v6, v157, v175
	v_fmac_f32_e32 v7, v157, v179
	v_fmac_f32_e32 v11, v157, v183
	global_load_dword v157, v172, s[52:53]
	s_add_u32 s52, s52, 0x6000
	s_addc_u32 s53, s53, 0
	s_waitcnt vmcnt(47)
	v_fmac_f32_e32 v6, v158, v176
	v_fmac_f32_e32 v7, v158, v180
	v_fmac_f32_e32 v11, v158, v184
	global_load_dword v158, v172, s[52:53]
	s_add_u32 s52, s52, 0x6000
	s_addc_u32 s53, s53, 0
	s_waitcnt vmcnt(47)
	v_fmac_f32_e32 v6, v159, v177
	v_fmac_f32_e32 v7, v159, v181
	v_fmac_f32_e32 v11, v159, v185
	global_load_dword v159, v172, s[52:53]
	s_add_u32 s52, s52, 0x6000
	s_addc_u32 s53, s53, 0
	ds_read_b128 v[174:177], v12 offset:384
	ds_read_b128 v[178:181], v12 offset:8576
	ds_read_b128 v[182:185], v12 offset:16768
	s_waitcnt vmcnt(47) lgkmcnt(9)
	v_fmac_f32_e32 v6, v160, v186
	v_fmac_f32_e32 v7, v160, v190
	v_fmac_f32_e32 v11, v160, v194
	global_load_dword v160, v172, s[52:53]
	s_add_u32 s52, s52, 0x6000
	s_addc_u32 s53, s53, 0
	s_waitcnt vmcnt(47)
	v_fmac_f32_e32 v6, v161, v187
	v_fmac_f32_e32 v7, v161, v191
	v_fmac_f32_e32 v11, v161, v195
	global_load_dword v161, v172, s[52:53]
	s_add_u32 s52, s52, 0x6000
	s_addc_u32 s53, s53, 0
	s_waitcnt vmcnt(47)
	v_fmac_f32_e32 v6, v162, v188
	v_fmac_f32_e32 v7, v162, v192
	v_fmac_f32_e32 v11, v162, v196
	global_load_dword v162, v172, s[52:53]
	s_add_u32 s52, s52, 0x6000
	s_addc_u32 s53, s53, 0
	s_waitcnt vmcnt(47)
	v_fmac_f32_e32 v6, v163, v189
	v_fmac_f32_e32 v7, v163, v193
	v_fmac_f32_e32 v11, v163, v197
	global_load_dword v163, v172, s[52:53]
	s_add_u32 s52, s52, 0x6000
	s_addc_u32 s53, s53, 0
	ds_read_b128 v[186:189], v12 offset:400
	ds_read_b128 v[190:193], v12 offset:8592
	ds_read_b128 v[194:197], v12 offset:16784
	s_waitcnt vmcnt(47) lgkmcnt(9)
	v_fmac_f32_e32 v6, v164, v198
	v_fmac_f32_e32 v7, v164, v202
	v_fmac_f32_e32 v11, v164, v206
	global_load_dword v164, v172, s[52:53]
	s_add_u32 s52, s52, 0x6000
	s_addc_u32 s53, s53, 0
	s_waitcnt vmcnt(47)
	v_fmac_f32_e32 v6, v165, v199
	v_fmac_f32_e32 v7, v165, v203
	v_fmac_f32_e32 v11, v165, v207
	global_load_dword v165, v172, s[52:53]
	s_add_u32 s52, s52, 0x6000
	s_addc_u32 s53, s53, 0
	s_waitcnt vmcnt(47)
	v_fmac_f32_e32 v6, v166, v200
	v_fmac_f32_e32 v7, v166, v204
	v_fmac_f32_e32 v11, v166, v208
	global_load_dword v166, v172, s[52:53]
	s_add_u32 s52, s52, 0x6000
	s_addc_u32 s53, s53, 0
	s_waitcnt vmcnt(47)
	v_fmac_f32_e32 v6, v167, v201
	v_fmac_f32_e32 v7, v167, v205
	v_fmac_f32_e32 v11, v167, v209
	global_load_dword v167, v172, s[52:53]
	s_add_u32 s52, s52, 0x6000
	s_addc_u32 s53, s53, 0
	ds_read_b128 v[198:201], v12 offset:416
	ds_read_b128 v[202:205], v12 offset:8608
	ds_read_b128 v[206:209], v12 offset:16800
	s_waitcnt vmcnt(47) lgkmcnt(9)
	v_fmac_f32_e32 v6, v168, v210
	v_fmac_f32_e32 v7, v168, v214
	v_fmac_f32_e32 v11, v168, v218
	global_load_dword v168, v172, s[52:53]
	s_add_u32 s52, s52, 0x6000
	s_addc_u32 s53, s53, 0
	s_waitcnt vmcnt(47)
	v_fmac_f32_e32 v6, v169, v211
	v_fmac_f32_e32 v7, v169, v215
	v_fmac_f32_e32 v11, v169, v219
	global_load_dword v169, v172, s[52:53]
	s_add_u32 s52, s52, 0x6000
	s_addc_u32 s53, s53, 0
	s_waitcnt vmcnt(47)
	v_fmac_f32_e32 v6, v170, v212
	v_fmac_f32_e32 v7, v170, v216
	v_fmac_f32_e32 v11, v170, v220
	global_load_dword v170, v172, s[52:53]
	s_add_u32 s52, s52, 0x6000
	s_addc_u32 s53, s53, 0
	s_waitcnt vmcnt(47)
	v_fmac_f32_e32 v6, v171, v213
	v_fmac_f32_e32 v7, v171, v217
	v_fmac_f32_e32 v11, v171, v221
	global_load_dword v171, v172, s[52:53]
	s_add_u32 s52, s52, 0x6000
	s_addc_u32 s53, s53, 0
	ds_read_b128 v[210:213], v12 offset:432
	ds_read_b128 v[214:217], v12 offset:8624
	ds_read_b128 v[218:221], v12 offset:16816
	s_waitcnt vmcnt(47) lgkmcnt(9)
; __device__ __forceinline__ void mod_item(PREF P, int l, int nt, float* sm) {
;     ...
;     const int col = tid & 63, kg = tid >> 6; const float* w = P.w_ada + (size_t)l * DM * 6144 + nt * 64 + col;
;     float a0 = 0.f, a1 = 0.f, a2 = 0.f;
; #pragma unroll 16
;     for (int k = kg * 256; k < kg * 256 + 256; ++k) { const float wv = w[(size_t)k * 6144]; a0 += sc[k] * wv; a1 += sc[2048 + k] * wv; a2 += sc[4096 + k] * wv; }
	v_fmac_f32_e32 v6, v124, v174
	v_fmac_f32_e32 v7, v124, v178
	v_fmac_f32_e32 v11, v124, v182
	global_load_dword v124, v172, s[52:53]
	s_add_u32 s52, s52, 0x6000
	s_addc_u32 s53, s53, 0
	s_waitcnt vmcnt(47)
	v_fmac_f32_e32 v6, v125, v175
	v_fmac_f32_e32 v7, v125, v179
	v_fmac_f32_e32 v11, v125, v183
	global_load_dword v125, v172, s[52:53]
	s_add_u32 s52, s52, 0x6000
	s_addc_u32 s53, s53, 0
	s_waitcnt vmcnt(47)
	v_fmac_f32_e32 v6, v126, v176
	v_fmac_f32_e32 v7, v126, v180
	v_fmac_f32_e32 v11, v126, v184
	global_load_dword v126, v172, s[52:53]
	s_add_u32 s52, s52, 0x6000
	s_addc_u32 s53, s53, 0
	s_waitcnt vmcnt(47)
	v_fmac_f32_e32 v6, v127, v177
	v_fmac_f32_e32 v7, v127, v181
	v_fmac_f32_e32 v11, v127, v185
	global_load_dword v127, v172, s[52:53]
	s_add_u32 s52, s52, 0x6000
	s_addc_u32 s53, s53, 0
	ds_read_b128 v[174:177], v12 offset:448
	ds_read_b128 v[178:181], v12 offset:8640
	ds_read_b128 v[182:185], v12 offset:16832
	s_waitcnt vmcnt(47) lgkmcnt(9)
	v_fmac_f32_e32 v6, v128, v186
	v_fmac_f32_e32 v7, v128, v190
	v_fmac_f32_e32 v11, v128, v194
	global_load_dword v128, v172, s[52:53]
	s_add_u32 s52, s52, 0x6000
	s_addc_u32 s53, s53, 0
	s_waitcnt vmcnt(47)
	v_fmac_f32_e32 v6, v129, v187
	v_fmac_f32_e32 v7, v129, v191
	v_fmac_f32_e32 v11, v129, v195
	global_load_dword v129, v172, s[52:53]
	s_add_u32 s52, s52, 0x6000
	s_addc_u32 s53, s53, 0
	s_waitcnt vmcnt(47)
	v_fmac_f32_e32 v6, v130, v188
	v_fmac_f32_e32 v7, v130, v192
	v_fmac_f32_e32 v11, v130, v196
	global_load_dword v130, v172, s[52:53]
	s_add_u32 s52, s52, 0x6000
	s_addc_u32 s53, s53, 0
	s_waitcnt vmcnt(47)
	v_fmac_f32_e32 v6, v131, v189
	v_fmac_f32_e32 v7, v131, v193
	v_fmac_f32_e32 v11, v131, v197
	global_load_dword v131, v172, s[52:53]
	s_add_u32 s52, s52, 0x6000
	s_addc_u32 s53, s53, 0
	ds_read_b128 v[186:189], v12 offset:464
	ds_read_b128 v[190:193], v12 offset:8656
	ds_read_b128 v[194:197], v12 offset:16848
	s_waitcnt vmcnt(47) lgkmcnt(9)
	v_fmac_f32_e32 v6, v132, v198
	v_fmac_f32_e32 v7, v132, v202
	v_fmac_f32_e32 v11, v132, v206
	global_load_dword v132, v172, s[52:53]
	s_add_u32 s52, s52, 0x6000
	s_addc_u32 s53, s53, 0
	s_waitcnt vmcnt(47)
	v_fmac_f32_e32 v6, v133, v199
	v_fmac_f32_e32 v7, v133, v203
	v_fmac_f32_e32 v11, v133, v207
	global_load_dword v133, v172, s[52:53]
	s_add_u32 s52, s52, 0x6000
	s_addc_u32 s53, s53, 0
	s_waitcnt vmcnt(47)
	v_fmac_f32_e32 v6, v134, v200
	v_fmac_f32_e32 v7, v134, v204
	v_fmac_f32_e32 v11, v134, v208
	global_load_dword v134, v172, s[52:53]
	s_add_u32 s52, s52, 0x6000
	s_addc_u32 s53, s53, 0
	s_waitcnt vmcnt(47)
	v_fmac_f32_e32 v6, v135, v201
	v_fmac_f32_e32 v7, v135, v205
	v_fmac_f32_e32 v11, v135, v209
	global_load_dword v135, v172, s[52:53]
	s_add_u32 s52, s52, 0x6000
	s_addc_u32 s53, s53, 0
	ds_read_b128 v[198:201], v12 offset:480
	ds_read_b128 v[202:205], v12 offset:8672
	ds_read_b128 v[206:209], v12 offset:16864
	s_waitcnt vmcnt(47) lgkmcnt(9)
	v_fmac_f32_e32 v6, v136, v210
	v_fmac_f32_e32 v7, v136, v214
	v_fmac_f32_e32 v11, v136, v218
	global_load_dword v136, v172, s[52:53]
	s_add_u32 s52, s52, 0x6000
	s_addc_u32 s53, s53, 0
	s_waitcnt vmcnt(47)
	v_fmac_f32_e32 v6, v137, v211
	v_fmac_f32_e32 v7, v137, v215
	v_fmac_f32_e32 v11, v137, v219
	global_load_dword v137, v172, s[52:53]
	s_add_u32 s52, s52, 0x6000
	s_addc_u32 s53, s53, 0
	s_waitcnt vmcnt(47)
	v_fmac_f32_e32 v6, v138, v212
	v_fmac_f32_e32 v7, v138, v216
	v_fmac_f32_e32 v11, v138, v220
	global_load_dword v138, v172, s[52:53]
	s_add_u32 s52, s52, 0x6000
	s_addc_u32 s53, s53, 0
	s_waitcnt vmcnt(47)
	v_fmac_f32_e32 v6, v139, v213
	v_fmac_f32_e32 v7, v139, v217
	v_fmac_f32_e32 v11, v139, v221
	global_load_dword v139, v172, s[52:53]
	s_add_u32 s52, s52, 0x6000
	s_addc_u32 s53, s53, 0
	ds_read_b128 v[210:213], v12 offset:496
	ds_read_b128 v[214:217], v12 offset:8688
	ds_read_b128 v[218:221], v12 offset:16880
	s_waitcnt vmcnt(47) lgkmcnt(9)
	v_fmac_f32_e32 v6, v140, v174
	v_fmac_f32_e32 v7, v140, v178
	v_fmac_f32_e32 v11, v140, v182
	global_load_dword v140, v172, s[52:53]
	s_add_u32 s52, s52, 0x6000
	s_addc_u32 s53, s53, 0
	s_waitcnt vmcnt(47)
	v_fmac_f32_e32 v6, v141, v175
	v_fmac_f32_e32 v7, v141, v179
	v_fmac_f32_e32 v11, v141, v183
	global_load_dword v141, v172, s[52:53]
	s_add_u32 s52, s52, 0x6000
	s_addc_u32 s53, s53, 0
	s_waitcnt vmcnt(47)
	v_fmac_f32_e32 v6, v142, v176
	v_fmac_f32_e32 v7, v142, v180
	v_fmac_f32_e32 v11, v142, v184
	global_load_dword v142, v172, s[52:53]
	s_add_u32 s52, s52, 0x6000
	s_addc_u32 s53, s53, 0
	s_waitcnt vmcnt(47)
	v_fmac_f32_e32 v6, v143, v177
	v_fmac_f32_e32 v7, v143, v181
	v_fmac_f32_e32 v11, v143, v185
	global_load_dword v143, v172, s[52:53]
	s_add_u32 s52, s52, 0x6000
	s_addc_u32 s53, s53, 0
	ds_read_b128 v[174:177], v12 offset:512
	ds_read_b128 v[178:181], v12 offset:8704
	ds_read_b128 v[182:185], v12 offset:16896
	s_waitcnt vmcnt(47) lgkmcnt(9)
	v_fmac_f32_e32 v6, v144, v186
	v_fmac_f32_e32 v7, v144, v190
	v_fmac_f32_e32 v11, v144, v194
	global_load_dword v144, v172, s[52:53]
	s_add_u32 s52, s52, 0x6000
	s_addc_u32 s53, s53, 0
	s_waitcnt vmcnt(47)
	v_fmac_f32_e32 v6, v145, v187
	v_fmac_f32_e32 v7, v145, v191
	v_fmac_f32_e32 v11, v145, v195
	global_load_dword v145, v172, s[52:53]
	s_add_u32 s52, s52, 0x6000
	s_addc_u32 s53, s53, 0
	s_waitcnt vmcnt(47)
	v_fmac_f32_e32 v6, v146, v188
	v_fmac_f32_e32 v7, v146, v192
	v_fmac_f32_e32 v11, v146, v196
	global_load_dword v146, v172, s[52:53]
	s_add_u32 s52, s52, 0x6000
	s_addc_u32 s53, s53, 0
	s_waitcnt vmcnt(47)
	v_fmac_f32_e32 v6, v147, v189
	v_fmac_f32_e32 v7, v147, v193
	v_fmac_f32_e32 v11, v147, v197
	global_load_dword v147, v172, s[52:53]
	s_add_u32 s52, s52, 0x6000
	s_addc_u32 s53, s53, 0
	ds_read_b128 v[186:189], v12 offset:528
	ds_read_b128 v[190:193], v12 offset:8720
	ds_read_b128 v[194:197], v12 offset:16912
	s_waitcnt vmcnt(47) lgkmcnt(9)
; __device__ __forceinline__ void mod_item(PREF P, int l, int nt, float* sm) {
;     ...
;     const int col = tid & 63, kg = tid >> 6; const float* w = P.w_ada + (size_t)l * DM * 6144 + nt * 64 + col;
;     float a0 = 0.f, a1 = 0.f, a2 = 0.f;
; #pragma unroll 16
;     for (int k = kg * 256; k < kg * 256 + 256; ++k) { const float wv = w[(size_t)k * 6144]; a0 += sc[k] * wv; a1 += sc[2048 + k] * wv; a2 += sc[4096 + k] * wv; }
	v_fmac_f32_e32 v6, v148, v198
	v_fmac_f32_e32 v7, v148, v202
	v_fmac_f32_e32 v11, v148, v206
	global_load_dword v148, v172, s[52:53]
	s_add_u32 s52, s52, 0x6000
	s_addc_u32 s53, s53, 0
	s_waitcnt vmcnt(47)
	v_fmac_f32_e32 v6, v149, v199
	v_fmac_f32_e32 v7, v149, v203
	v_fmac_f32_e32 v11, v149, v207
	global_load_dword v149, v172, s[52:53]
	s_add_u32 s52, s52, 0x6000
	s_addc_u32 s53, s53, 0
	s_waitcnt vmcnt(47)
	v_fmac_f32_e32 v6, v150, v200
	v_fmac_f32_e32 v7, v150, v204
	v_fmac_f32_e32 v11, v150, v208
	global_load_dword v150, v172, s[52:53]
	s_add_u32 s52, s52, 0x6000
	s_addc_u32 s53, s53, 0
	s_waitcnt vmcnt(47)
	v_fmac_f32_e32 v6, v151, v201
	v_fmac_f32_e32 v7, v151, v205
	v_fmac_f32_e32 v11, v151, v209
	global_load_dword v151, v172, s[52:53]
	s_add_u32 s52, s52, 0x6000
	s_addc_u32 s53, s53, 0
	ds_read_b128 v[198:201], v12 offset:544
	ds_read_b128 v[202:205], v12 offset:8736
	ds_read_b128 v[206:209], v12 offset:16928
	s_waitcnt vmcnt(47) lgkmcnt(9)
	v_fmac_f32_e32 v6, v152, v210
	v_fmac_f32_e32 v7, v152, v214
	v_fmac_f32_e32 v11, v152, v218
	global_load_dword v152, v172, s[52:53]
	s_add_u32 s52, s52, 0x6000
	s_addc_u32 s53, s53, 0
	s_waitcnt vmcnt(47)
	v_fmac_f32_e32 v6, v153, v211
	v_fmac_f32_e32 v7, v153, v215
	v_fmac_f32_e32 v11, v153, v219
	global_load_dword v153, v172, s[52:53]
	s_add_u32 s52, s52, 0x6000
	s_addc_u32 s53, s53, 0
	s_waitcnt vmcnt(47)
	v_fmac_f32_e32 v6, v154, v212
	v_fmac_f32_e32 v7, v154, v216
	v_fmac_f32_e32 v11, v154, v220
	global_load_dword v154, v172, s[52:53]
	s_add_u32 s52, s52, 0x6000
	s_addc_u32 s53, s53, 0
	s_waitcnt vmcnt(47)
	v_fmac_f32_e32 v6, v155, v213
	v_fmac_f32_e32 v7, v155, v217
	v_fmac_f32_e32 v11, v155, v221
	global_load_dword v155, v172, s[52:53]
	s_add_u32 s52, s52, 0x6000
	s_addc_u32 s53, s53, 0
	ds_read_b128 v[210:213], v12 offset:560
	ds_read_b128 v[214:217], v12 offset:8752
	ds_read_b128 v[218:221], v12 offset:16944
	s_waitcnt vmcnt(47) lgkmcnt(9)
	v_fmac_f32_e32 v6, v156, v174
	v_fmac_f32_e32 v7, v156, v178
	v_fmac_f32_e32 v11, v156, v182
	global_load_dword v156, v172, s[52:53]
	s_add_u32 s52, s52, 0x6000
	s_addc_u32 s53, s53, 0
	s_waitcnt vmcnt(47)
	v_fmac_f32_e32 v6, v157, v175
	v_fmac_f32_e32 v7, v157, v179
	v_fmac_f32_e32 v11, v157, v183
	global_load_dword v157, v172, s[52:53]
	s_add_u32 s52, s52, 0x6000
	s_addc_u32 s53, s53, 0
	s_waitcnt vmcnt(47)
	v_fmac_f32_e32 v6, v158, v176
	v_fmac_f32_e32 v7, v158, v180
	v_fmac_f32_e32 v11, v158, v184
	global_load_dword v158, v172, s[52:53]
	s_add_u32 s52, s52, 0x6000
	s_addc_u32 s53, s53, 0
	s_waitcnt vmcnt(47)
	v_fmac_f32_e32 v6, v159, v177
	v_fmac_f32_e32 v7, v159, v181
	v_fmac_f32_e32 v11, v159, v185
	global_load_dword v159, v172, s[52:53]
	s_add_u32 s52, s52, 0x6000
	s_addc_u32 s53, s53, 0
	ds_read_b128 v[174:177], v12 offset:576
	ds_read_b128 v[178:181], v12 offset:8768
	ds_read_b128 v[182:185], v12 offset:16960
	s_waitcnt vmcnt(47) lgkmcnt(9)
	v_fmac_f32_e32 v6, v160, v186
	v_fmac_f32_e32 v7, v160, v190
	v_fmac_f32_e32 v11, v160, v194
	global_load_dword v160, v172, s[52:53]
	s_add_u32 s52, s52, 0x6000
	s_addc_u32 s53, s53, 0
	s_waitcnt vmcnt(47)
	v_fmac_f32_e32 v6, v161, v187
	v_fmac_f32_e32 v7, v161, v191
	v_fmac_f32_e32 v11, v161, v195
	global_load_dword v161, v172, s[52:53]
	s_add_u32 s52, s52, 0x6000
	s_addc_u32 s53, s53, 0
	s_waitcnt vmcnt(47)
	v_fmac_f32_e32 v6, v162, v188
	v_fmac_f32_e32 v7, v162, v192
	v_fmac_f32_e32 v11, v162, v196
	global_load_dword v162, v172, s[52:53]
	s_add_u32 s52, s52, 0x6000
	s_addc_u32 s53, s53, 0
	s_waitcnt vmcnt(47)
	v_fmac_f32_e32 v6, v163, v189
	v_fmac_f32_e32 v7, v163, v193
	v_fmac_f32_e32 v11, v163, v197
	global_load_dword v163, v172, s[52:53]
	s_add_u32 s52, s52, 0x6000
	s_addc_u32 s53, s53, 0
	ds_read_b128 v[186:189], v12 offset:592
	ds_read_b128 v[190:193], v12 offset:8784
	ds_read_b128 v[194:197], v12 offset:16976
	s_waitcnt vmcnt(47) lgkmcnt(9)
	v_fmac_f32_e32 v6, v164, v198
	v_fmac_f32_e32 v7, v164, v202
	v_fmac_f32_e32 v11, v164, v206
	global_load_dword v164, v172, s[52:53]
	s_add_u32 s52, s52, 0x6000
	s_addc_u32 s53, s53, 0
	s_waitcnt vmcnt(47)
	v_fmac_f32_e32 v6, v165, v199
	v_fmac_f32_e32 v7, v165, v203
	v_fmac_f32_e32 v11, v165, v207
	global_load_dword v165, v172, s[52:53]
	s_add_u32 s52, s52, 0x6000
	s_addc_u32 s53, s53, 0
	s_waitcnt vmcnt(47)
	v_fmac_f32_e32 v6, v166, v200
	v_fmac_f32_e32 v7, v166, v204
	v_fmac_f32_e32 v11, v166, v208
	global_load_dword v166, v172, s[52:53]
	s_add_u32 s52, s52, 0x6000
	s_addc_u32 s53, s53, 0
	s_waitcnt vmcnt(47)
	v_fmac_f32_e32 v6, v167, v201
	v_fmac_f32_e32 v7, v167, v205
	v_fmac_f32_e32 v11, v167, v209
	global_load_dword v167, v172, s[52:53]
	s_add_u32 s52, s52, 0x6000
	s_addc_u32 s53, s53, 0
	ds_read_b128 v[198:201], v12 offset:608
	ds_read_b128 v[202:205], v12 offset:8800
	ds_read_b128 v[206:209], v12 offset:16992
	s_waitcnt vmcnt(47) lgkmcnt(9)
	v_fmac_f32_e32 v6, v168, v210
	v_fmac_f32_e32 v7, v168, v214
	v_fmac_f32_e32 v11, v168, v218
	global_load_dword v168, v172, s[52:53]
	s_add_u32 s52, s52, 0x6000
	s_addc_u32 s53, s53, 0
	s_waitcnt vmcnt(47)
	v_fmac_f32_e32 v6, v169, v211
	v_fmac_f32_e32 v7, v169, v215
	v_fmac_f32_e32 v11, v169, v219
	global_load_dword v169, v172, s[52:53]
	s_add_u32 s52, s52, 0x6000
	s_addc_u32 s53, s53, 0
	s_waitcnt vmcnt(47)
	v_fmac_f32_e32 v6, v170, v212
	v_fmac_f32_e32 v7, v170, v216
	v_fmac_f32_e32 v11, v170, v220
	global_load_dword v170, v172, s[52:53]
	s_add_u32 s52, s52, 0x6000
	s_addc_u32 s53, s53, 0
	s_waitcnt vmcnt(47)
	v_fmac_f32_e32 v6, v171, v213
	v_fmac_f32_e32 v7, v171, v217
	v_fmac_f32_e32 v11, v171, v221
	global_load_dword v171, v172, s[52:53]
	s_add_u32 s52, s52, 0x6000
	s_addc_u32 s53, s53, 0
	ds_read_b128 v[210:213], v12 offset:624
	ds_read_b128 v[214:217], v12 offset:8816
	ds_read_b128 v[218:221], v12 offset:17008
	s_waitcnt vmcnt(47) lgkmcnt(9)
; __device__ __forceinline__ void mod_item(PREF P, int l, int nt, float* sm) {
;     ...
;     const int col = tid & 63, kg = tid >> 6; const float* w = P.w_ada + (size_t)l * DM * 6144 + nt * 64 + col;
;     float a0 = 0.f, a1 = 0.f, a2 = 0.f;
; #pragma unroll 16
;     for (int k = kg * 256; k < kg * 256 + 256; ++k) { const float wv = w[(size_t)k * 6144]; a0 += sc[k] * wv; a1 += sc[2048 + k] * wv; a2 += sc[4096 + k] * wv; }
	v_fmac_f32_e32 v6, v124, v174
	v_fmac_f32_e32 v7, v124, v178
	v_fmac_f32_e32 v11, v124, v182
	global_load_dword v124, v172, s[52:53]
	s_add_u32 s52, s52, 0x6000
	s_addc_u32 s53, s53, 0
	s_waitcnt vmcnt(47)
	v_fmac_f32_e32 v6, v125, v175
	v_fmac_f32_e32 v7, v125, v179
	v_fmac_f32_e32 v11, v125, v183
	global_load_dword v125, v172, s[52:53]
	s_add_u32 s52, s52, 0x6000
	s_addc_u32 s53, s53, 0
	s_waitcnt vmcnt(47)
	v_fmac_f32_e32 v6, v126, v176
	v_fmac_f32_e32 v7, v126, v180
	v_fmac_f32_e32 v11, v126, v184
	global_load_dword v126, v172, s[52:53]
	s_add_u32 s52, s52, 0x6000
	s_addc_u32 s53, s53, 0
	s_waitcnt vmcnt(47)
	v_fmac_f32_e32 v6, v127, v177
	v_fmac_f32_e32 v7, v127, v181
	v_fmac_f32_e32 v11, v127, v185
	global_load_dword v127, v172, s[52:53]
	s_add_u32 s52, s52, 0x6000
	s_addc_u32 s53, s53, 0
	ds_read_b128 v[174:177], v12 offset:640
	ds_read_b128 v[178:181], v12 offset:8832
	ds_read_b128 v[182:185], v12 offset:17024
	s_waitcnt vmcnt(47) lgkmcnt(9)
	v_fmac_f32_e32 v6, v128, v186
	v_fmac_f32_e32 v7, v128, v190
	v_fmac_f32_e32 v11, v128, v194
	global_load_dword v128, v172, s[52:53]
	s_add_u32 s52, s52, 0x6000
	s_addc_u32 s53, s53, 0
	s_waitcnt vmcnt(47)
	v_fmac_f32_e32 v6, v129, v187
	v_fmac_f32_e32 v7, v129, v191
	v_fmac_f32_e32 v11, v129, v195
	global_load_dword v129, v172, s[52:53]
	s_add_u32 s52, s52, 0x6000
	s_addc_u32 s53, s53, 0
	s_waitcnt vmcnt(47)
	v_fmac_f32_e32 v6, v130, v188
	v_fmac_f32_e32 v7, v130, v192
	v_fmac_f32_e32 v11, v130, v196
	global_load_dword v130, v172, s[52:53]
	s_add_u32 s52, s52, 0x6000
	s_addc_u32 s53, s53, 0
	s_waitcnt vmcnt(47)
	v_fmac_f32_e32 v6, v131, v189
	v_fmac_f32_e32 v7, v131, v193
	v_fmac_f32_e32 v11, v131, v197
	global_load_dword v131, v172, s[52:53]
	s_add_u32 s52, s52, 0x6000
	s_addc_u32 s53, s53, 0
	ds_read_b128 v[186:189], v12 offset:656
	ds_read_b128 v[190:193], v12 offset:8848
	ds_read_b128 v[194:197], v12 offset:17040
	s_waitcnt vmcnt(47) lgkmcnt(9)
	v_fmac_f32_e32 v6, v132, v198
	v_fmac_f32_e32 v7, v132, v202
	v_fmac_f32_e32 v11, v132, v206
	global_load_dword v132, v172, s[52:53]
	s_add_u32 s52, s52, 0x6000
	s_addc_u32 s53, s53, 0
	s_waitcnt vmcnt(47)
	v_fmac_f32_e32 v6, v133, v199
	v_fmac_f32_e32 v7, v133, v203
	v_fmac_f32_e32 v11, v133, v207
	global_load_dword v133, v172, s[52:53]
	s_add_u32 s52, s52, 0x6000
	s_addc_u32 s53, s53, 0
	s_waitcnt vmcnt(47)
	v_fmac_f32_e32 v6, v134, v200
	v_fmac_f32_e32 v7, v134, v204
	v_fmac_f32_e32 v11, v134, v208
	global_load_dword v134, v172, s[52:53]
	s_add_u32 s52, s52, 0x6000
	s_addc_u32 s53, s53, 0
	s_waitcnt vmcnt(47)
	v_fmac_f32_e32 v6, v135, v201
	v_fmac_f32_e32 v7, v135, v205
	v_fmac_f32_e32 v11, v135, v209
	global_load_dword v135, v172, s[52:53]
	s_add_u32 s52, s52, 0x6000
	s_addc_u32 s53, s53, 0
	ds_read_b128 v[198:201], v12 offset:672
	ds_read_b128 v[202:205], v12 offset:8864
	ds_read_b128 v[206:209], v12 offset:17056
	s_waitcnt vmcnt(47) lgkmcnt(9)
	v_fmac_f32_e32 v6, v136, v210
	v_fmac_f32_e32 v7, v136, v214
	v_fmac_f32_e32 v11, v136, v218
	global_load_dword v136, v172, s[52:53]
	s_add_u32 s52, s52, 0x6000
	s_addc_u32 s53, s53, 0
	s_waitcnt vmcnt(47)
	v_fmac_f32_e32 v6, v137, v211
	v_fmac_f32_e32 v7, v137, v215
	v_fmac_f32_e32 v11, v137, v219
	global_load_dword v137, v172, s[52:53]
	s_add_u32 s52, s52, 0x6000
	s_addc_u32 s53, s53, 0
	s_waitcnt vmcnt(47)
	v_fmac_f32_e32 v6, v138, v212
	v_fmac_f32_e32 v7, v138, v216
	v_fmac_f32_e32 v11, v138, v220
	global_load_dword v138, v172, s[52:53]
	s_add_u32 s52, s52, 0x6000
	s_addc_u32 s53, s53, 0
	s_waitcnt vmcnt(47)
	v_fmac_f32_e32 v6, v139, v213
	v_fmac_f32_e32 v7, v139, v217
	v_fmac_f32_e32 v11, v139, v221
	global_load_dword v139, v172, s[52:53]
	s_add_u32 s52, s52, 0x6000
	s_addc_u32 s53, s53, 0
	ds_read_b128 v[210:213], v12 offset:688
	ds_read_b128 v[214:217], v12 offset:8880
	ds_read_b128 v[218:221], v12 offset:17072
	s_waitcnt vmcnt(47) lgkmcnt(9)
	v_fmac_f32_e32 v6, v140, v174
	v_fmac_f32_e32 v7, v140, v178
	v_fmac_f32_e32 v11, v140, v182
	global_load_dword v140, v172, s[52:53]
	s_add_u32 s52, s52, 0x6000
	s_addc_u32 s53, s53, 0
	s_waitcnt vmcnt(47)
	v_fmac_f32_e32 v6, v141, v175
	v_fmac_f32_e32 v7, v141, v179
	v_fmac_f32_e32 v11, v141, v183
	global_load_dword v141, v172, s[52:53]
	s_add_u32 s52, s52, 0x6000
	s_addc_u32 s53, s53, 0
	s_waitcnt vmcnt(47)
	v_fmac_f32_e32 v6, v142, v176
	v_fmac_f32_e32 v7, v142, v180
	v_fmac_f32_e32 v11, v142, v184
	global_load_dword v142, v172, s[52:53]
	s_add_u32 s52, s52, 0x6000
	s_addc_u32 s53, s53, 0
	s_waitcnt vmcnt(47)
	v_fmac_f32_e32 v6, v143, v177
	v_fmac_f32_e32 v7, v143, v181
	v_fmac_f32_e32 v11, v143, v185
	global_load_dword v143, v172, s[52:53]
	s_add_u32 s52, s52, 0x6000
	s_addc_u32 s53, s53, 0
	ds_read_b128 v[174:177], v12 offset:704
	ds_read_b128 v[178:181], v12 offset:8896
	ds_read_b128 v[182:185], v12 offset:17088
	s_waitcnt vmcnt(47) lgkmcnt(9)
	v_fmac_f32_e32 v6, v144, v186
	v_fmac_f32_e32 v7, v144, v190
	v_fmac_f32_e32 v11, v144, v194
	global_load_dword v144, v172, s[52:53]
	s_add_u32 s52, s52, 0x6000
	s_addc_u32 s53, s53, 0
	s_waitcnt vmcnt(47)
	v_fmac_f32_e32 v6, v145, v187
	v_fmac_f32_e32 v7, v145, v191
	v_fmac_f32_e32 v11, v145, v195
	global_load_dword v145, v172, s[52:53]
	s_add_u32 s52, s52, 0x6000
	s_addc_u32 s53, s53, 0
	s_waitcnt vmcnt(47)
	v_fmac_f32_e32 v6, v146, v188
	v_fmac_f32_e32 v7, v146, v192
	v_fmac_f32_e32 v11, v146, v196
	global_load_dword v146, v172, s[52:53]
	s_add_u32 s52, s52, 0x6000
	s_addc_u32 s53, s53, 0
	s_waitcnt vmcnt(47)
	v_fmac_f32_e32 v6, v147, v189
	v_fmac_f32_e32 v7, v147, v193
	v_fmac_f32_e32 v11, v147, v197
	global_load_dword v147, v172, s[52:53]
	s_add_u32 s52, s52, 0x6000
	s_addc_u32 s53, s53, 0
	ds_read_b128 v[186:189], v12 offset:720
	ds_read_b128 v[190:193], v12 offset:8912
	ds_read_b128 v[194:197], v12 offset:17104
	s_waitcnt vmcnt(47) lgkmcnt(9)
; __device__ __forceinline__ void mod_item(PREF P, int l, int nt, float* sm) {
;     ...
;     const int col = tid & 63, kg = tid >> 6; const float* w = P.w_ada + (size_t)l * DM * 6144 + nt * 64 + col;
;     float a0 = 0.f, a1 = 0.f, a2 = 0.f;
; #pragma unroll 16
;     for (int k = kg * 256; k < kg * 256 + 256; ++k) { const float wv = w[(size_t)k * 6144]; a0 += sc[k] * wv; a1 += sc[2048 + k] * wv; a2 += sc[4096 + k] * wv; }
	v_fmac_f32_e32 v6, v148, v198
	v_fmac_f32_e32 v7, v148, v202
	v_fmac_f32_e32 v11, v148, v206
	global_load_dword v148, v172, s[52:53]
	s_add_u32 s52, s52, 0x6000
	s_addc_u32 s53, s53, 0
	s_waitcnt vmcnt(47)
	v_fmac_f32_e32 v6, v149, v199
	v_fmac_f32_e32 v7, v149, v203
	v_fmac_f32_e32 v11, v149, v207
	global_load_dword v149, v172, s[52:53]
	s_add_u32 s52, s52, 0x6000
	s_addc_u32 s53, s53, 0
	s_waitcnt vmcnt(47)
	v_fmac_f32_e32 v6, v150, v200
	v_fmac_f32_e32 v7, v150, v204
	v_fmac_f32_e32 v11, v150, v208
	global_load_dword v150, v172, s[52:53]
	s_add_u32 s52, s52, 0x6000
	s_addc_u32 s53, s53, 0
	s_waitcnt vmcnt(47)
	v_fmac_f32_e32 v6, v151, v201
	v_fmac_f32_e32 v7, v151, v205
	v_fmac_f32_e32 v11, v151, v209
	global_load_dword v151, v172, s[52:53]
	s_add_u32 s52, s52, 0x6000
	s_addc_u32 s53, s53, 0
	ds_read_b128 v[198:201], v12 offset:736
	ds_read_b128 v[202:205], v12 offset:8928
	ds_read_b128 v[206:209], v12 offset:17120
	s_waitcnt vmcnt(47) lgkmcnt(9)
	v_fmac_f32_e32 v6, v152, v210
	v_fmac_f32_e32 v7, v152, v214
	v_fmac_f32_e32 v11, v152, v218
	global_load_dword v152, v172, s[52:53]
	s_add_u32 s52, s52, 0x6000
	s_addc_u32 s53, s53, 0
	s_waitcnt vmcnt(47)
	v_fmac_f32_e32 v6, v153, v211
	v_fmac_f32_e32 v7, v153, v215
	v_fmac_f32_e32 v11, v153, v219
	global_load_dword v153, v172, s[52:53]
	s_add_u32 s52, s52, 0x6000
	s_addc_u32 s53, s53, 0
	s_waitcnt vmcnt(47)
	v_fmac_f32_e32 v6, v154, v212
	v_fmac_f32_e32 v7, v154, v216
	v_fmac_f32_e32 v11, v154, v220
	global_load_dword v154, v172, s[52:53]
	s_add_u32 s52, s52, 0x6000
	s_addc_u32 s53, s53, 0
	s_waitcnt vmcnt(47)
	v_fmac_f32_e32 v6, v155, v213
	v_fmac_f32_e32 v7, v155, v217
	v_fmac_f32_e32 v11, v155, v221
	global_load_dword v155, v172, s[52:53]
	s_add_u32 s52, s52, 0x6000
	s_addc_u32 s53, s53, 0
	ds_read_b128 v[210:213], v12 offset:752
	ds_read_b128 v[214:217], v12 offset:8944
	ds_read_b128 v[218:221], v12 offset:17136
	s_waitcnt vmcnt(47) lgkmcnt(9)
	v_fmac_f32_e32 v6, v156, v174
	v_fmac_f32_e32 v7, v156, v178
	v_fmac_f32_e32 v11, v156, v182
	global_load_dword v156, v172, s[52:53]
	s_add_u32 s52, s52, 0x6000
	s_addc_u32 s53, s53, 0
	s_waitcnt vmcnt(47)
	v_fmac_f32_e32 v6, v157, v175
	v_fmac_f32_e32 v7, v157, v179
	v_fmac_f32_e32 v11, v157, v183
	global_load_dword v157, v172, s[52:53]
	s_add_u32 s52, s52, 0x6000
	s_addc_u32 s53, s53, 0
	s_waitcnt vmcnt(47)
	v_fmac_f32_e32 v6, v158, v176
	v_fmac_f32_e32 v7, v158, v180
	v_fmac_f32_e32 v11, v158, v184
	global_load_dword v158, v172, s[52:53]
	s_add_u32 s52, s52, 0x6000
	s_addc_u32 s53, s53, 0
	s_waitcnt vmcnt(47)
	v_fmac_f32_e32 v6, v159, v177
	v_fmac_f32_e32 v7, v159, v181
	v_fmac_f32_e32 v11, v159, v185
	global_load_dword v159, v172, s[52:53]
	s_add_u32 s52, s52, 0x6000
	s_addc_u32 s53, s53, 0
	ds_read_b128 v[174:177], v12 offset:768
	ds_read_b128 v[178:181], v12 offset:8960
	ds_read_b128 v[182:185], v12 offset:17152
	s_waitcnt vmcnt(47) lgkmcnt(9)
	v_fmac_f32_e32 v6, v160, v186
	v_fmac_f32_e32 v7, v160, v190
	v_fmac_f32_e32 v11, v160, v194
	global_load_dword v160, v172, s[52:53]
	s_add_u32 s52, s52, 0x6000
	s_addc_u32 s53, s53, 0
	s_waitcnt vmcnt(47)
	v_fmac_f32_e32 v6, v161, v187
	v_fmac_f32_e32 v7, v161, v191
	v_fmac_f32_e32 v11, v161, v195
	global_load_dword v161, v172, s[52:53]
	s_add_u32 s52, s52, 0x6000
	s_addc_u32 s53, s53, 0
	s_waitcnt vmcnt(47)
	v_fmac_f32_e32 v6, v162, v188
	v_fmac_f32_e32 v7, v162, v192
	v_fmac_f32_e32 v11, v162, v196
	global_load_dword v162, v172, s[52:53]
	s_add_u32 s52, s52, 0x6000
	s_addc_u32 s53, s53, 0
	s_waitcnt vmcnt(47)
	v_fmac_f32_e32 v6, v163, v189
	v_fmac_f32_e32 v7, v163, v193
	v_fmac_f32_e32 v11, v163, v197
	global_load_dword v163, v172, s[52:53]
	s_add_u32 s52, s52, 0x6000
	s_addc_u32 s53, s53, 0
	ds_read_b128 v[186:189], v12 offset:784
	ds_read_b128 v[190:193], v12 offset:8976
	ds_read_b128 v[194:197], v12 offset:17168
	s_waitcnt vmcnt(47) lgkmcnt(9)
	v_fmac_f32_e32 v6, v164, v198
	v_fmac_f32_e32 v7, v164, v202
	v_fmac_f32_e32 v11, v164, v206
	global_load_dword v164, v172, s[52:53]
	s_add_u32 s52, s52, 0x6000
	s_addc_u32 s53, s53, 0
	s_waitcnt vmcnt(47)
	v_fmac_f32_e32 v6, v165, v199
	v_fmac_f32_e32 v7, v165, v203
	v_fmac_f32_e32 v11, v165, v207
	global_load_dword v165, v172, s[52:53]
	s_add_u32 s52, s52, 0x6000
	s_addc_u32 s53, s53, 0
	s_waitcnt vmcnt(47)
	v_fmac_f32_e32 v6, v166, v200
	v_fmac_f32_e32 v7, v166, v204
	v_fmac_f32_e32 v11, v166, v208
	global_load_dword v166, v172, s[52:53]
	s_add_u32 s52, s52, 0x6000
	s_addc_u32 s53, s53, 0
	s_waitcnt vmcnt(47)
	v_fmac_f32_e32 v6, v167, v201
	v_fmac_f32_e32 v7, v167, v205
	v_fmac_f32_e32 v11, v167, v209
	global_load_dword v167, v172, s[52:53]
	s_add_u32 s52, s52, 0x6000
	s_addc_u32 s53, s53, 0
	ds_read_b128 v[198:201], v12 offset:800
	ds_read_b128 v[202:205], v12 offset:8992
	ds_read_b128 v[206:209], v12 offset:17184
	s_waitcnt vmcnt(47) lgkmcnt(9)
	v_fmac_f32_e32 v6, v168, v210
	v_fmac_f32_e32 v7, v168, v214
	v_fmac_f32_e32 v11, v168, v218
	global_load_dword v168, v172, s[52:53]
	s_add_u32 s52, s52, 0x6000
	s_addc_u32 s53, s53, 0
	s_waitcnt vmcnt(47)
	v_fmac_f32_e32 v6, v169, v211
	v_fmac_f32_e32 v7, v169, v215
	v_fmac_f32_e32 v11, v169, v219
	global_load_dword v169, v172, s[52:53]
	s_add_u32 s52, s52, 0x6000
	s_addc_u32 s53, s53, 0
	s_waitcnt vmcnt(47)
	v_fmac_f32_e32 v6, v170, v212
	v_fmac_f32_e32 v7, v170, v216
	v_fmac_f32_e32 v11, v170, v220
	global_load_dword v170, v172, s[52:53]
	s_add_u32 s52, s52, 0x6000
	s_addc_u32 s53, s53, 0
	s_waitcnt vmcnt(47)
	v_fmac_f32_e32 v6, v171, v213
	v_fmac_f32_e32 v7, v171, v217
	v_fmac_f32_e32 v11, v171, v221
	global_load_dword v171, v172, s[52:53]
	s_add_u32 s52, s52, 0x6000
	s_addc_u32 s53, s53, 0
	ds_read_b128 v[210:213], v12 offset:816
	ds_read_b128 v[214:217], v12 offset:9008
	ds_read_b128 v[218:221], v12 offset:17200
	s_waitcnt vmcnt(47) lgkmcnt(9)
; __device__ __forceinline__ void mod_item(PREF P, int l, int nt, float* sm) {
;     ...
;     const int col = tid & 63, kg = tid >> 6; const float* w = P.w_ada + (size_t)l * DM * 6144 + nt * 64 + col;
;     float a0 = 0.f, a1 = 0.f, a2 = 0.f;
; #pragma unroll 16
;     for (int k = kg * 256; k < kg * 256 + 256; ++k) { const float wv = w[(size_t)k * 6144]; a0 += sc[k] * wv; a1 += sc[2048 + k] * wv; a2 += sc[4096 + k] * wv; }
	v_fmac_f32_e32 v6, v124, v174
	v_fmac_f32_e32 v7, v124, v178
	v_fmac_f32_e32 v11, v124, v182
	global_load_dword v124, v172, s[52:53]
	s_add_u32 s52, s52, 0x6000
	s_addc_u32 s53, s53, 0
	s_waitcnt vmcnt(47)
	v_fmac_f32_e32 v6, v125, v175
	v_fmac_f32_e32 v7, v125, v179
	v_fmac_f32_e32 v11, v125, v183
	global_load_dword v125, v172, s[52:53]
	s_add_u32 s52, s52, 0x6000
	s_addc_u32 s53, s53, 0
	s_waitcnt vmcnt(47)
	v_fmac_f32_e32 v6, v126, v176
	v_fmac_f32_e32 v7, v126, v180
	v_fmac_f32_e32 v11, v126, v184
	global_load_dword v126, v172, s[52:53]
	s_add_u32 s52, s52, 0x6000
	s_addc_u32 s53, s53, 0
	s_waitcnt vmcnt(47)
	v_fmac_f32_e32 v6, v127, v177
	v_fmac_f32_e32 v7, v127, v181
	v_fmac_f32_e32 v11, v127, v185
	global_load_dword v127, v172, s[52:53]
	s_add_u32 s52, s52, 0x6000
	s_addc_u32 s53, s53, 0
	ds_read_b128 v[174:177], v12 offset:832
	ds_read_b128 v[178:181], v12 offset:9024
	ds_read_b128 v[182:185], v12 offset:17216
	s_waitcnt vmcnt(47) lgkmcnt(9)
	v_fmac_f32_e32 v6, v128, v186
	v_fmac_f32_e32 v7, v128, v190
	v_fmac_f32_e32 v11, v128, v194
	global_load_dword v128, v172, s[52:53]
	s_add_u32 s52, s52, 0x6000
	s_addc_u32 s53, s53, 0
	s_waitcnt vmcnt(47)
	v_fmac_f32_e32 v6, v129, v187
	v_fmac_f32_e32 v7, v129, v191
	v_fmac_f32_e32 v11, v129, v195
	global_load_dword v129, v172, s[52:53]
	s_add_u32 s52, s52, 0x6000
	s_addc_u32 s53, s53, 0
	s_waitcnt vmcnt(47)
	v_fmac_f32_e32 v6, v130, v188
	v_fmac_f32_e32 v7, v130, v192
	v_fmac_f32_e32 v11, v130, v196
	global_load_dword v130, v172, s[52:53]
	s_add_u32 s52, s52, 0x6000
	s_addc_u32 s53, s53, 0
	s_waitcnt vmcnt(47)
	v_fmac_f32_e32 v6, v131, v189
	v_fmac_f32_e32 v7, v131, v193
	v_fmac_f32_e32 v11, v131, v197
	global_load_dword v131, v172, s[52:53]
	s_add_u32 s52, s52, 0x6000
	s_addc_u32 s53, s53, 0
	ds_read_b128 v[186:189], v12 offset:848
	ds_read_b128 v[190:193], v12 offset:9040
	ds_read_b128 v[194:197], v12 offset:17232
	s_waitcnt vmcnt(47) lgkmcnt(9)
	v_fmac_f32_e32 v6, v132, v198
	v_fmac_f32_e32 v7, v132, v202
	v_fmac_f32_e32 v11, v132, v206
	global_load_dword v132, v172, s[52:53]
	s_add_u32 s52, s52, 0x6000
	s_addc_u32 s53, s53, 0
	s_waitcnt vmcnt(47)
	v_fmac_f32_e32 v6, v133, v199
	v_fmac_f32_e32 v7, v133, v203
	v_fmac_f32_e32 v11, v133, v207
	global_load_dword v133, v172, s[52:53]
	s_add_u32 s52, s52, 0x6000
	s_addc_u32 s53, s53, 0
	s_waitcnt vmcnt(47)
	v_fmac_f32_e32 v6, v134, v200
	v_fmac_f32_e32 v7, v134, v204
	v_fmac_f32_e32 v11, v134, v208
	global_load_dword v134, v172, s[52:53]
	s_add_u32 s52, s52, 0x6000
	s_addc_u32 s53, s53, 0
	s_waitcnt vmcnt(47)
	v_fmac_f32_e32 v6, v135, v201
	v_fmac_f32_e32 v7, v135, v205
	v_fmac_f32_e32 v11, v135, v209
	global_load_dword v135, v172, s[52:53]
	s_add_u32 s52, s52, 0x6000
	s_addc_u32 s53, s53, 0
	ds_read_b128 v[198:201], v12 offset:864
	ds_read_b128 v[202:205], v12 offset:9056
	ds_read_b128 v[206:209], v12 offset:17248
	s_waitcnt vmcnt(47) lgkmcnt(9)
	v_fmac_f32_e32 v6, v136, v210
	v_fmac_f32_e32 v7, v136, v214
	v_fmac_f32_e32 v11, v136, v218
	global_load_dword v136, v172, s[52:53]
	s_add_u32 s52, s52, 0x6000
	s_addc_u32 s53, s53, 0
	s_waitcnt vmcnt(47)
	v_fmac_f32_e32 v6, v137, v211
	v_fmac_f32_e32 v7, v137, v215
	v_fmac_f32_e32 v11, v137, v219
	global_load_dword v137, v172, s[52:53]
	s_add_u32 s52, s52, 0x6000
	s_addc_u32 s53, s53, 0
	s_waitcnt vmcnt(47)
	v_fmac_f32_e32 v6, v138, v212
	v_fmac_f32_e32 v7, v138, v216
	v_fmac_f32_e32 v11, v138, v220
	global_load_dword v138, v172, s[52:53]
	s_add_u32 s52, s52, 0x6000
	s_addc_u32 s53, s53, 0
	s_waitcnt vmcnt(47)
	v_fmac_f32_e32 v6, v139, v213
	v_fmac_f32_e32 v7, v139, v217
	v_fmac_f32_e32 v11, v139, v221
	global_load_dword v139, v172, s[52:53]
	s_add_u32 s52, s52, 0x6000
	s_addc_u32 s53, s53, 0
	ds_read_b128 v[210:213], v12 offset:880
	ds_read_b128 v[214:217], v12 offset:9072
	ds_read_b128 v[218:221], v12 offset:17264
	s_waitcnt vmcnt(47) lgkmcnt(9)
	v_fmac_f32_e32 v6, v140, v174
	v_fmac_f32_e32 v7, v140, v178
	v_fmac_f32_e32 v11, v140, v182
	s_waitcnt vmcnt(46)
	v_fmac_f32_e32 v6, v141, v175
	v_fmac_f32_e32 v7, v141, v179
	v_fmac_f32_e32 v11, v141, v183
	s_waitcnt vmcnt(45)
	v_fmac_f32_e32 v6, v142, v176
	v_fmac_f32_e32 v7, v142, v180
	v_fmac_f32_e32 v11, v142, v184
	s_waitcnt vmcnt(44)
	v_fmac_f32_e32 v6, v143, v177
	v_fmac_f32_e32 v7, v143, v181
	v_fmac_f32_e32 v11, v143, v185
	ds_read_b128 v[174:177], v12 offset:896
	ds_read_b128 v[178:181], v12 offset:9088
	ds_read_b128 v[182:185], v12 offset:17280
	s_waitcnt vmcnt(43) lgkmcnt(9)
	v_fmac_f32_e32 v6, v144, v186
	v_fmac_f32_e32 v7, v144, v190
	v_fmac_f32_e32 v11, v144, v194
	s_waitcnt vmcnt(42)
	v_fmac_f32_e32 v6, v145, v187
	v_fmac_f32_e32 v7, v145, v191
	v_fmac_f32_e32 v11, v145, v195
	s_waitcnt vmcnt(41)
	v_fmac_f32_e32 v6, v146, v188
	v_fmac_f32_e32 v7, v146, v192
	v_fmac_f32_e32 v11, v146, v196
	s_waitcnt vmcnt(40)
	v_fmac_f32_e32 v6, v147, v189
	v_fmac_f32_e32 v7, v147, v193
	v_fmac_f32_e32 v11, v147, v197
	ds_read_b128 v[186:189], v12 offset:912
	ds_read_b128 v[190:193], v12 offset:9104
	ds_read_b128 v[194:197], v12 offset:17296
	s_waitcnt vmcnt(39) lgkmcnt(9)
	v_fmac_f32_e32 v6, v148, v198
	v_fmac_f32_e32 v7, v148, v202
	v_fmac_f32_e32 v11, v148, v206
	s_waitcnt vmcnt(38)
	v_fmac_f32_e32 v6, v149, v199
	v_fmac_f32_e32 v7, v149, v203
	v_fmac_f32_e32 v11, v149, v207
	s_waitcnt vmcnt(37)
	v_fmac_f32_e32 v6, v150, v200
	v_fmac_f32_e32 v7, v150, v204
	v_fmac_f32_e32 v11, v150, v208
	s_waitcnt vmcnt(36)
	v_fmac_f32_e32 v6, v151, v201
	v_fmac_f32_e32 v7, v151, v205
	v_fmac_f32_e32 v11, v151, v209
	ds_read_b128 v[198:201], v12 offset:928
	ds_read_b128 v[202:205], v12 offset:9120
	ds_read_b128 v[206:209], v12 offset:17312
	s_waitcnt vmcnt(35) lgkmcnt(9)
; __device__ __forceinline__ void mod_item(PREF P, int l, int nt, float* sm) {
;     ...
;     for (int k = kg * 256; k < kg * 256 + 256; ++k) { const float wv = w[(size_t)k * 6144]; a0 += sc[k] * wv; a1 += sc[2048 + k] * wv; a2 += sc[4096 + k] * wv; }
;     red[(kg * 3 + 0) * 64 + col] = a0; red[(kg * 3 + 1) * 64 + col] = a1; red[(kg * 3 + 2) * 64 + col] = a2;
;     __syncthreads();
;     if (tid < 192) { const int r = tid >> 6, c = tid & 63; float s = 0.f;
; #pragma unroll
;         for (int k = 0; k < 8; ++k) s += red[(k * 3 + r) * 64 + c];
;         float* MOD = (float*)(P.ws + l * SZ_LAYER + LO_MOD); MOD[r * 6144 + nt * 64 + c] = s + P.b_ada[l * 6144 + nt * 64 + c]; }
	v_fmac_f32_e32 v6, v152, v210
	v_fmac_f32_e32 v7, v152, v214
	v_fmac_f32_e32 v11, v152, v218
	s_waitcnt vmcnt(34)
	v_fmac_f32_e32 v6, v153, v211
	v_fmac_f32_e32 v7, v153, v215
	v_fmac_f32_e32 v11, v153, v219
	s_waitcnt vmcnt(33)
	v_fmac_f32_e32 v6, v154, v212
	v_fmac_f32_e32 v7, v154, v216
	v_fmac_f32_e32 v11, v154, v220
	s_waitcnt vmcnt(32)
	v_fmac_f32_e32 v6, v155, v213
	v_fmac_f32_e32 v7, v155, v217
	v_fmac_f32_e32 v11, v155, v221
	ds_read_b128 v[210:213], v12 offset:944
	ds_read_b128 v[214:217], v12 offset:9136
	ds_read_b128 v[218:221], v12 offset:17328
	s_waitcnt vmcnt(31) lgkmcnt(9)
	v_fmac_f32_e32 v6, v156, v174
	v_fmac_f32_e32 v7, v156, v178
	v_fmac_f32_e32 v11, v156, v182
	s_waitcnt vmcnt(30)
	v_fmac_f32_e32 v6, v157, v175
	v_fmac_f32_e32 v7, v157, v179
	v_fmac_f32_e32 v11, v157, v183
	s_waitcnt vmcnt(29)
	v_fmac_f32_e32 v6, v158, v176
	v_fmac_f32_e32 v7, v158, v180
	v_fmac_f32_e32 v11, v158, v184
	s_waitcnt vmcnt(28)
	v_fmac_f32_e32 v6, v159, v177
	v_fmac_f32_e32 v7, v159, v181
	v_fmac_f32_e32 v11, v159, v185
	ds_read_b128 v[174:177], v12 offset:960
	ds_read_b128 v[178:181], v12 offset:9152
	ds_read_b128 v[182:185], v12 offset:17344
	s_waitcnt vmcnt(27) lgkmcnt(9)
	v_fmac_f32_e32 v6, v160, v186
	v_fmac_f32_e32 v7, v160, v190
	v_fmac_f32_e32 v11, v160, v194
	s_waitcnt vmcnt(26)
	v_fmac_f32_e32 v6, v161, v187
	v_fmac_f32_e32 v7, v161, v191
	v_fmac_f32_e32 v11, v161, v195
	s_waitcnt vmcnt(25)
	v_fmac_f32_e32 v6, v162, v188
	v_fmac_f32_e32 v7, v162, v192
	v_fmac_f32_e32 v11, v162, v196
	s_waitcnt vmcnt(24)
	v_fmac_f32_e32 v6, v163, v189
	v_fmac_f32_e32 v7, v163, v193
	v_fmac_f32_e32 v11, v163, v197
	ds_read_b128 v[186:189], v12 offset:976
	ds_read_b128 v[190:193], v12 offset:9168
	ds_read_b128 v[194:197], v12 offset:17360
	s_waitcnt vmcnt(23) lgkmcnt(9)
	v_fmac_f32_e32 v6, v164, v198
	v_fmac_f32_e32 v7, v164, v202
	v_fmac_f32_e32 v11, v164, v206
	s_waitcnt vmcnt(22)
	v_fmac_f32_e32 v6, v165, v199
	v_fmac_f32_e32 v7, v165, v203
	v_fmac_f32_e32 v11, v165, v207
	s_waitcnt vmcnt(21)
	v_fmac_f32_e32 v6, v166, v200
	v_fmac_f32_e32 v7, v166, v204
	v_fmac_f32_e32 v11, v166, v208
	s_waitcnt vmcnt(20)
	v_fmac_f32_e32 v6, v167, v201
	v_fmac_f32_e32 v7, v167, v205
	v_fmac_f32_e32 v11, v167, v209
	ds_read_b128 v[198:201], v12 offset:992
	ds_read_b128 v[202:205], v12 offset:9184
	ds_read_b128 v[206:209], v12 offset:17376
	s_waitcnt vmcnt(19) lgkmcnt(9)
	v_fmac_f32_e32 v6, v168, v210
	v_fmac_f32_e32 v7, v168, v214
	v_fmac_f32_e32 v11, v168, v218
	s_waitcnt vmcnt(18)
	v_fmac_f32_e32 v6, v169, v211
	v_fmac_f32_e32 v7, v169, v215
	v_fmac_f32_e32 v11, v169, v219
	s_waitcnt vmcnt(17)
	v_fmac_f32_e32 v6, v170, v212
	v_fmac_f32_e32 v7, v170, v216
	v_fmac_f32_e32 v11, v170, v220
	s_waitcnt vmcnt(16)
	v_fmac_f32_e32 v6, v171, v213
	v_fmac_f32_e32 v7, v171, v217
	v_fmac_f32_e32 v11, v171, v221
	ds_read_b128 v[210:213], v12 offset:1008
	ds_read_b128 v[214:217], v12 offset:9200
	ds_read_b128 v[218:221], v12 offset:17392
	s_waitcnt vmcnt(15) lgkmcnt(9)
	v_fmac_f32_e32 v6, v124, v174
	v_fmac_f32_e32 v7, v124, v178
	v_fmac_f32_e32 v11, v124, v182
	s_waitcnt vmcnt(14)
	v_fmac_f32_e32 v6, v125, v175
	v_fmac_f32_e32 v7, v125, v179
	v_fmac_f32_e32 v11, v125, v183
	s_waitcnt vmcnt(13)
	v_fmac_f32_e32 v6, v126, v176
	v_fmac_f32_e32 v7, v126, v180
	v_fmac_f32_e32 v11, v126, v184
	s_waitcnt vmcnt(12)
	v_fmac_f32_e32 v6, v127, v177
	v_fmac_f32_e32 v7, v127, v181
	v_fmac_f32_e32 v11, v127, v185
	s_waitcnt vmcnt(11) lgkmcnt(6)
	v_fmac_f32_e32 v6, v128, v186
	v_fmac_f32_e32 v7, v128, v190
	v_fmac_f32_e32 v11, v128, v194
	s_waitcnt vmcnt(10)
	v_fmac_f32_e32 v6, v129, v187
	v_fmac_f32_e32 v7, v129, v191
	v_fmac_f32_e32 v11, v129, v195
	s_waitcnt vmcnt(9)
	v_fmac_f32_e32 v6, v130, v188
	v_fmac_f32_e32 v7, v130, v192
	v_fmac_f32_e32 v11, v130, v196
	s_waitcnt vmcnt(8)
	v_fmac_f32_e32 v6, v131, v189
	v_fmac_f32_e32 v7, v131, v193
	v_fmac_f32_e32 v11, v131, v197
	s_waitcnt vmcnt(7) lgkmcnt(3)
	v_fmac_f32_e32 v6, v132, v198
	v_fmac_f32_e32 v7, v132, v202
	v_fmac_f32_e32 v11, v132, v206
	s_waitcnt vmcnt(6)
	v_fmac_f32_e32 v6, v133, v199
	v_fmac_f32_e32 v7, v133, v203
	v_fmac_f32_e32 v11, v133, v207
	s_waitcnt vmcnt(5)
	v_fmac_f32_e32 v6, v134, v200
	v_fmac_f32_e32 v7, v134, v204
	v_fmac_f32_e32 v11, v134, v208
	s_waitcnt vmcnt(4)
	v_fmac_f32_e32 v6, v135, v201
	v_fmac_f32_e32 v7, v135, v205
	v_fmac_f32_e32 v11, v135, v209
	s_waitcnt vmcnt(3) lgkmcnt(0)
	v_fmac_f32_e32 v6, v136, v210
	v_fmac_f32_e32 v7, v136, v214
	v_fmac_f32_e32 v11, v136, v218
	s_waitcnt vmcnt(2)
	v_fmac_f32_e32 v6, v137, v211
	v_fmac_f32_e32 v7, v137, v215
	v_fmac_f32_e32 v11, v137, v219
	s_waitcnt vmcnt(1)
	v_fmac_f32_e32 v6, v138, v212
	v_fmac_f32_e32 v7, v138, v216
	v_fmac_f32_e32 v11, v138, v220
	s_waitcnt vmcnt(0)
	v_fmac_f32_e32 v6, v139, v213
	v_fmac_f32_e32 v7, v139, v217
	v_fmac_f32_e32 v11, v139, v221
	v_add_u32_e32 v12, 0x400, v12
	s_mov_b32 s9, 0xc000
	s_mov_b32 s51, 0x12000
	s_mov_b32 s52, 0x18000
	s_mov_b32 s53, 0x1e000
	s_mov_b32 s54, 0x24000
	s_mov_b32 s55, 0x2a000
	s_mov_b32 s56, 0x30000
	s_mov_b32 s57, 0x36000
	s_mov_b32 s58, 0x3c000
	s_mov_b32 s62, 0x42000
	s_mov_b32 s63, 0x48000
	s_mov_b32 s66, 0x4e000
	s_mov_b32 s67, 0x54000
	s_mov_b32 s68, 0x5a000
	s_mov_b32 s46, 0x600000
	s_mov_b32 s47, 0
	s_cmp_eq_u32 s46, 0x600000
	s_movk_i32 s9, 0x300
	v_mul_lo_u32 v5, v3, s9
	v_lshlrev_b32_e32 v4, 2, v1
	s_movk_i32 s9, 0xc0
	v_add3_u32 v5, 16, v5, v4
	v_cmp_gt_i32_e32 vcc, s9, v2
	ds_write2st64_b32 v5, v6, v7 offset0:96 offset1:97
	ds_write_b32 v5, v11 offset:25088
	s_waitcnt lgkmcnt(0)
	s_barrier
	s_and_saveexec_b64 s[46:47], vcc
	s_cbranch_execz .LBB0_103
	s_and_b64 s[52:53], s[44:45], exec
	s_cselect_b32 s9, 0x6e22000, 0
	s_add_u32 s52, s34, s9
	s_addc_u32 s53, s35, 0
	s_load_dwordx2 s[54:55], s[6:7], 0x28
	s_and_b64 s[44:45], s[44:45], exec
	s_cselect_b32 s9, 0x1800, 0
	s_add_i32 s9, s86, s9
	v_or_b32_e32 v22, s9, v1
	s_waitcnt lgkmcnt(0)
	v_lshl_add_u64 v[6:7], v[22:23], 2, s[54:55]
	global_load_dword v12, v[6:7], off
	v_add3_u32 v8, 16, v4, v10
	s_movk_i32 s9, 0x1800
	v_mul_lo_u32 v10, v3, s9
	ds_read2st64_b32 v[2:3], v8 offset0:96 offset1:99
	ds_read2st64_b32 v[4:5], v8 offset0:102 offset1:105
	ds_read2st64_b32 v[6:7], v8 offset0:108 offset1:111
	ds_read2st64_b32 v[8:9], v8 offset0:114 offset1:117
	v_add_u32_e32 v10, s86, v10
	v_or_b32_e32 v10, v10, v1
	s_waitcnt lgkmcnt(3)
	v_add_f32_e32 v1, 0, v2
	v_add_f32_e32 v1, v1, v3
	s_waitcnt lgkmcnt(2)
	v_add_f32_e32 v1, v1, v4
	v_add_f32_e32 v1, v1, v5
	s_waitcnt lgkmcnt(1)
	v_add_f32_e32 v1, v1, v6
	v_ashrrev_i32_e32 v11, 31, v10
	v_add_f32_e32 v1, v1, v7
	v_lshl_add_u64 v[10:11], v[10:11], 2, s[52:53]
	s_waitcnt lgkmcnt(0)
	v_add_f32_e32 v1, v1, v8
	v_add_co_u32_e32 v10, vcc, 0x6e10000, v10
	v_add_f32_e32 v1, v1, v9
	s_nop 0
	v_addc_co_u32_e32 v11, vcc, 0, v11, vcc
	s_waitcnt vmcnt(0)
	v_add_f32_e32 v1, v1, v12
	global_store_dword v[10:11], v1, off

; #define LAS __attribute__((address_space(3)))
; template <int KW, bool YST>
; __device__ __forceinline__ void ssm_stage_lds(PREF P, const int l, const int wi, unsigned char* shm, const int tid) {
;     ...
;     for (int ch = tid; ch < 128 * CPR; ch += 512) { const int row = ch / CPR, c = ch % CPR; const u32x4 v = *(const u32x4*)(D + (size_t)row * KW + c * 8);
;         *(LAS u32x4*)(lds + row * (KW * 2) + ((c ^ (row & 15)) << 4)) = v; }
.LBB0_496:
	v_ashrrev_i32_e32 v4, 31, v3
	v_lshrrev_b32_e32 v4, 27, v4
	v_add_u32_e32 v14, v3, v4
	v_ashrrev_i32_e32 v8, 5, v14
	v_ashrrev_i32_e32 v9, 31, v8
	v_lshlrev_b32_e32 v6, 8, v8
	v_lshlrev_b64 v[4:5], 9, v[8:9]
	v_sub_u32_e32 v6, v2, v6
	v_lshl_add_u64 v[4:5], s[16:17], 0, v[4:5]
	v_ashrrev_i32_e32 v7, 31, v6
	v_lshl_add_u64 v[4:5], v[6:7], 1, v[4:5]
	global_load_dwordx4 v[40:43], v[4:5], off
	v_and_b32_e32 v14, 0xfffffe0, v14
	v_sub_u32_e32 v14, v3, v14
	v_lshlrev_b32_e32 v15, 9, v8
	v_bitop3_b32 v8, v8, v14, 15 bitop3:0x6c
	v_add_u32_e32 v9, 0x200, v3
	v_lshlrev_b32_e32 v8, 4, v8
	v_mov_b32_e32 v3, v9
	v_add_u32_e32 v2, 0x1000, v2
	v_add3_u32 v72, 16, v15, v8
	v_ashrrev_i32_e32 v4, 31, v3
	v_lshrrev_b32_e32 v4, 27, v4
	v_add_u32_e32 v14, v3, v4
	v_ashrrev_i32_e32 v8, 5, v14
	v_ashrrev_i32_e32 v9, 31, v8
	v_lshlrev_b32_e32 v6, 8, v8
	v_lshlrev_b64 v[4:5], 9, v[8:9]
	v_sub_u32_e32 v6, v2, v6
	v_lshl_add_u64 v[4:5], s[16:17], 0, v[4:5]
	v_ashrrev_i32_e32 v7, 31, v6
	v_lshl_add_u64 v[4:5], v[6:7], 1, v[4:5]
	global_load_dwordx4 v[44:47], v[4:5], off
	v_and_b32_e32 v14, 0xfffffe0, v14
	v_sub_u32_e32 v14, v3, v14
	v_lshlrev_b32_e32 v15, 9, v8
	v_bitop3_b32 v8, v8, v14, 15 bitop3:0x6c
	v_add_u32_e32 v9, 0x200, v3
	v_lshlrev_b32_e32 v8, 4, v8
	v_mov_b32_e32 v3, v9
	v_add_u32_e32 v2, 0x1000, v2
	v_add3_u32 v73, 16, v15, v8
	v_ashrrev_i32_e32 v4, 31, v3
	v_lshrrev_b32_e32 v4, 27, v4
	v_add_u32_e32 v14, v3, v4
	v_ashrrev_i32_e32 v8, 5, v14
	v_ashrrev_i32_e32 v9, 31, v8
	v_lshlrev_b32_e32 v6, 8, v8
	v_lshlrev_b64 v[4:5], 9, v[8:9]
	v_sub_u32_e32 v6, v2, v6
	v_lshl_add_u64 v[4:5], s[16:17], 0, v[4:5]
	v_ashrrev_i32_e32 v7, 31, v6
	v_lshl_add_u64 v[4:5], v[6:7], 1, v[4:5]
	global_load_dwordx4 v[48:51], v[4:5], off
	v_and_b32_e32 v14, 0xfffffe0, v14
	v_sub_u32_e32 v14, v3, v14
	v_lshlrev_b32_e32 v15, 9, v8
	v_bitop3_b32 v8, v8, v14, 15 bitop3:0x6c
	v_add_u32_e32 v9, 0x200, v3
	v_lshlrev_b32_e32 v8, 4, v8
	v_mov_b32_e32 v3, v9
	v_add_u32_e32 v2, 0x1000, v2
	v_add3_u32 v74, 16, v15, v8
	v_ashrrev_i32_e32 v4, 31, v3
	v_lshrrev_b32_e32 v4, 27, v4
	v_add_u32_e32 v14, v3, v4
	v_ashrrev_i32_e32 v8, 5, v14
	v_ashrrev_i32_e32 v9, 31, v8
	v_lshlrev_b32_e32 v6, 8, v8
	v_lshlrev_b64 v[4:5], 9, v[8:9]
	v_sub_u32_e32 v6, v2, v6
	v_lshl_add_u64 v[4:5], s[16:17], 0, v[4:5]
	v_ashrrev_i32_e32 v7, 31, v6
	v_lshl_add_u64 v[4:5], v[6:7], 1, v[4:5]
	global_load_dwordx4 v[52:55], v[4:5], off
	v_and_b32_e32 v14, 0xfffffe0, v14
	v_sub_u32_e32 v14, v3, v14
	v_lshlrev_b32_e32 v15, 9, v8
	v_bitop3_b32 v8, v8, v14, 15 bitop3:0x6c
	v_add_u32_e32 v9, 0x200, v3
	v_lshlrev_b32_e32 v8, 4, v8
	v_mov_b32_e32 v3, v9
	v_add_u32_e32 v2, 0x1000, v2
	v_add3_u32 v75, 16, v15, v8
	v_ashrrev_i32_e32 v4, 31, v3
	v_lshrrev_b32_e32 v4, 27, v4
	v_add_u32_e32 v14, v3, v4
	v_ashrrev_i32_e32 v8, 5, v14
	v_ashrrev_i32_e32 v9, 31, v8
	v_lshlrev_b32_e32 v6, 8, v8
	v_lshlrev_b64 v[4:5], 9, v[8:9]
	v_sub_u32_e32 v6, v2, v6
	v_lshl_add_u64 v[4:5], s[16:17], 0, v[4:5]
	v_ashrrev_i32_e32 v7, 31, v6
	v_lshl_add_u64 v[4:5], v[6:7], 1, v[4:5]
	global_load_dwordx4 v[56:59], v[4:5], off
	v_and_b32_e32 v14, 0xfffffe0, v14
	v_sub_u32_e32 v14, v3, v14
	v_lshlrev_b32_e32 v15, 9, v8
	v_bitop3_b32 v8, v8, v14, 15 bitop3:0x6c
	v_add_u32_e32 v9, 0x200, v3
	v_lshlrev_b32_e32 v8, 4, v8
	v_mov_b32_e32 v3, v9
	v_add_u32_e32 v2, 0x1000, v2
	v_add3_u32 v76, 16, v15, v8
	v_ashrrev_i32_e32 v4, 31, v3
	v_lshrrev_b32_e32 v4, 27, v4
	v_add_u32_e32 v14, v3, v4
	v_ashrrev_i32_e32 v8, 5, v14
	v_ashrrev_i32_e32 v9, 31, v8
	v_lshlrev_b32_e32 v6, 8, v8
	v_lshlrev_b64 v[4:5], 9, v[8:9]
	v_sub_u32_e32 v6, v2, v6
	v_lshl_add_u64 v[4:5], s[16:17], 0, v[4:5]
	v_ashrrev_i32_e32 v7, 31, v6
	v_lshl_add_u64 v[4:5], v[6:7], 1, v[4:5]
	global_load_dwordx4 v[60:63], v[4:5], off
	v_and_b32_e32 v14, 0xfffffe0, v14
	v_sub_u32_e32 v14, v3, v14
	v_lshlrev_b32_e32 v15, 9, v8
	v_bitop3_b32 v8, v8, v14, 15 bitop3:0x6c
	v_add_u32_e32 v9, 0x200, v3
	v_lshlrev_b32_e32 v8, 4, v8
	v_mov_b32_e32 v3, v9
	v_add_u32_e32 v2, 0x1000, v2
	v_add3_u32 v77, 16, v15, v8
	v_ashrrev_i32_e32 v4, 31, v3
	v_lshrrev_b32_e32 v4, 27, v4
	v_add_u32_e32 v14, v3, v4
	v_ashrrev_i32_e32 v8, 5, v14
	v_ashrrev_i32_e32 v9, 31, v8
	v_lshlrev_b32_e32 v6, 8, v8
	v_lshlrev_b64 v[4:5], 9, v[8:9]
	v_sub_u32_e32 v6, v2, v6
	v_lshl_add_u64 v[4:5], s[16:17], 0, v[4:5]
	v_ashrrev_i32_e32 v7, 31, v6
	v_lshl_add_u64 v[4:5], v[6:7], 1, v[4:5]
	global_load_dwordx4 v[64:67], v[4:5], off
	v_and_b32_e32 v14, 0xfffffe0, v14
	v_sub_u32_e32 v14, v3, v14
	v_lshlrev_b32_e32 v15, 9, v8
	v_bitop3_b32 v8, v8, v14, 15 bitop3:0x6c
	v_add_u32_e32 v9, 0x200, v3
	v_lshlrev_b32_e32 v8, 4, v8
	v_mov_b32_e32 v3, v9
	v_add_u32_e32 v2, 0x1000, v2
	v_add3_u32 v78, 16, v15, v8
	v_ashrrev_i32_e32 v4, 31, v3
	v_lshrrev_b32_e32 v4, 27, v4
	v_add_u32_e32 v14, v3, v4
	v_ashrrev_i32_e32 v8, 5, v14
	v_ashrrev_i32_e32 v9, 31, v8
	v_lshlrev_b32_e32 v6, 8, v8
	v_lshlrev_b64 v[4:5], 9, v[8:9]
	v_sub_u32_e32 v6, v2, v6
	v_lshl_add_u64 v[4:5], s[16:17], 0, v[4:5]
	v_ashrrev_i32_e32 v7, 31, v6
	v_lshl_add_u64 v[4:5], v[6:7], 1, v[4:5]
	global_load_dwordx4 v[68:71], v[4:5], off
	v_and_b32_e32 v14, 0xfffffe0, v14
	v_sub_u32_e32 v14, v3, v14
	v_lshlrev_b32_e32 v15, 9, v8
	v_bitop3_b32 v8, v8, v14, 15 bitop3:0x6c
	v_add_u32_e32 v9, 0x200, v3
	v_lshlrev_b32_e32 v8, 4, v8
	v_mov_b32_e32 v3, v9
	v_add_u32_e32 v2, 0x1000, v2
	v_add3_u32 v79, 16, v15, v8
	s_waitcnt vmcnt(7)
	ds_write_b128 v72, v[40:43]
	s_waitcnt vmcnt(6)
	ds_write_b128 v73, v[44:47]
	s_waitcnt vmcnt(5)
	ds_write_b128 v74, v[48:51]
	s_waitcnt vmcnt(4)
	ds_write_b128 v75, v[52:55]
	s_waitcnt vmcnt(3)
	ds_write_b128 v76, v[56:59]
	s_waitcnt vmcnt(2)
	ds_write_b128 v77, v[60:63]
	s_waitcnt vmcnt(1)
	ds_write_b128 v78, v[64:67]
	s_waitcnt vmcnt(0)
	ds_write_b128 v79, v[68:71]

; #define LAS __attribute__((address_space(3)))
; template <int KW, bool YST>
; __device__ __forceinline__ void ssm_stage_lds(PREF P, const int l, const int wi, unsigned char* shm, const int tid) {
;     ...
;     for (int ch = tid; ch < 128 * CPR; ch += 512) { const int row = ch / CPR, c = ch % CPR; const u32x4 v = *(const u32x4*)(D + (size_t)row * KW + c * 8);
;         *(LAS u32x4*)(lds + row * (KW * 2) + ((c ^ (row & 15)) << 4)) = v; }
.LBB0_645:
	v_ashrrev_i32_e32 v4, 31, v3
	v_lshrrev_b32_e32 v4, 26, v4
	v_add_u32_e32 v10, v3, v4
	v_ashrrev_i32_e32 v8, 6, v10
	v_ashrrev_i32_e32 v9, 31, v8
	v_lshlrev_b32_e32 v6, 9, v8
	v_lshlrev_b64 v[4:5], 10, v[8:9]
	v_sub_u32_e32 v6, v2, v6
	v_lshl_add_u64 v[4:5], s[14:15], 0, v[4:5]
	v_ashrrev_i32_e32 v7, 31, v6
	v_lshl_add_u64 v[4:5], v[6:7], 1, v[4:5]
	global_load_dwordx4 v[80:83], v[4:5], off
	v_and_b32_e32 v10, 0xfffffc0, v10
	v_sub_u32_e32 v10, v3, v10
	v_lshlrev_b32_e32 v11, 10, v8
	v_bitop3_b32 v8, v8, v10, 15 bitop3:0x6c
	v_add_u32_e32 v9, 0x200, v3
	v_lshlrev_b32_e32 v8, 4, v8
	v_mov_b32_e32 v3, v9
	v_add_u32_e32 v2, 0x1000, v2
	v_add3_u32 v40, 16, v11, v8
	v_ashrrev_i32_e32 v4, 31, v3
	v_lshrrev_b32_e32 v4, 26, v4
	v_add_u32_e32 v10, v3, v4
	v_ashrrev_i32_e32 v8, 6, v10
	v_ashrrev_i32_e32 v9, 31, v8
	v_lshlrev_b32_e32 v6, 9, v8
	v_lshlrev_b64 v[4:5], 10, v[8:9]
	v_sub_u32_e32 v6, v2, v6
	v_lshl_add_u64 v[4:5], s[14:15], 0, v[4:5]
	v_ashrrev_i32_e32 v7, 31, v6
	v_lshl_add_u64 v[4:5], v[6:7], 1, v[4:5]
	global_load_dwordx4 v[84:87], v[4:5], off
	v_and_b32_e32 v10, 0xfffffc0, v10
	v_sub_u32_e32 v10, v3, v10
	v_lshlrev_b32_e32 v11, 10, v8
	v_bitop3_b32 v8, v8, v10, 15 bitop3:0x6c
	v_add_u32_e32 v9, 0x200, v3
	v_lshlrev_b32_e32 v8, 4, v8
	v_mov_b32_e32 v3, v9
	v_add_u32_e32 v2, 0x1000, v2
	v_add3_u32 v41, 16, v11, v8
	v_ashrrev_i32_e32 v4, 31, v3
	v_lshrrev_b32_e32 v4, 26, v4
	v_add_u32_e32 v10, v3, v4
	v_ashrrev_i32_e32 v8, 6, v10
	v_ashrrev_i32_e32 v9, 31, v8
	v_lshlrev_b32_e32 v6, 9, v8
	v_lshlrev_b64 v[4:5], 10, v[8:9]
	v_sub_u32_e32 v6, v2, v6
	v_lshl_add_u64 v[4:5], s[14:15], 0, v[4:5]
	v_ashrrev_i32_e32 v7, 31, v6
	v_lshl_add_u64 v[4:5], v[6:7], 1, v[4:5]
	global_load_dwordx4 v[88:91], v[4:5], off
	v_and_b32_e32 v10, 0xfffffc0, v10
	v_sub_u32_e32 v10, v3, v10
	v_lshlrev_b32_e32 v11, 10, v8
	v_bitop3_b32 v8, v8, v10, 15 bitop3:0x6c
	v_add_u32_e32 v9, 0x200, v3
	v_lshlrev_b32_e32 v8, 4, v8
	v_mov_b32_e32 v3, v9
	v_add_u32_e32 v2, 0x1000, v2
	v_add3_u32 v42, 16, v11, v8
	v_ashrrev_i32_e32 v4, 31, v3
	v_lshrrev_b32_e32 v4, 26, v4
	v_add_u32_e32 v10, v3, v4
	v_ashrrev_i32_e32 v8, 6, v10
	v_ashrrev_i32_e32 v9, 31, v8
	v_lshlrev_b32_e32 v6, 9, v8
	v_lshlrev_b64 v[4:5], 10, v[8:9]
	v_sub_u32_e32 v6, v2, v6
	v_lshl_add_u64 v[4:5], s[14:15], 0, v[4:5]
	v_ashrrev_i32_e32 v7, 31, v6
	v_lshl_add_u64 v[4:5], v[6:7], 1, v[4:5]
	global_load_dwordx4 v[92:95], v[4:5], off
	v_and_b32_e32 v10, 0xfffffc0, v10
	v_sub_u32_e32 v10, v3, v10
	v_lshlrev_b32_e32 v11, 10, v8
	v_bitop3_b32 v8, v8, v10, 15 bitop3:0x6c
	v_add_u32_e32 v9, 0x200, v3
	v_lshlrev_b32_e32 v8, 4, v8
	v_mov_b32_e32 v3, v9
	v_add_u32_e32 v2, 0x1000, v2
	v_add3_u32 v43, 16, v11, v8
	v_ashrrev_i32_e32 v4, 31, v3
	v_lshrrev_b32_e32 v4, 26, v4
	v_add_u32_e32 v10, v3, v4
	v_ashrrev_i32_e32 v8, 6, v10
	v_ashrrev_i32_e32 v9, 31, v8
	v_lshlrev_b32_e32 v6, 9, v8
	v_lshlrev_b64 v[4:5], 10, v[8:9]
	v_sub_u32_e32 v6, v2, v6
	v_lshl_add_u64 v[4:5], s[14:15], 0, v[4:5]
	v_ashrrev_i32_e32 v7, 31, v6
	v_lshl_add_u64 v[4:5], v[6:7], 1, v[4:5]
	global_load_dwordx4 v[96:99], v[4:5], off
	v_and_b32_e32 v10, 0xfffffc0, v10
	v_sub_u32_e32 v10, v3, v10
	v_lshlrev_b32_e32 v11, 10, v8
	v_bitop3_b32 v8, v8, v10, 15 bitop3:0x6c
	v_add_u32_e32 v9, 0x200, v3
	v_lshlrev_b32_e32 v8, 4, v8
	v_mov_b32_e32 v3, v9
	v_add_u32_e32 v2, 0x1000, v2
	v_add3_u32 v44, 16, v11, v8
	v_ashrrev_i32_e32 v4, 31, v3
	v_lshrrev_b32_e32 v4, 26, v4
	v_add_u32_e32 v10, v3, v4
	v_ashrrev_i32_e32 v8, 6, v10
	v_ashrrev_i32_e32 v9, 31, v8
	v_lshlrev_b32_e32 v6, 9, v8
	v_lshlrev_b64 v[4:5], 10, v[8:9]
	v_sub_u32_e32 v6, v2, v6
	v_lshl_add_u64 v[4:5], s[14:15], 0, v[4:5]
	v_ashrrev_i32_e32 v7, 31, v6
	v_lshl_add_u64 v[4:5], v[6:7], 1, v[4:5]
	global_load_dwordx4 v[100:103], v[4:5], off
	v_and_b32_e32 v10, 0xfffffc0, v10
	v_sub_u32_e32 v10, v3, v10
	v_lshlrev_b32_e32 v11, 10, v8
	v_bitop3_b32 v8, v8, v10, 15 bitop3:0x6c
	v_add_u32_e32 v9, 0x200, v3
	v_lshlrev_b32_e32 v8, 4, v8
	v_mov_b32_e32 v3, v9
	v_add_u32_e32 v2, 0x1000, v2
	v_add3_u32 v45, 16, v11, v8
	v_ashrrev_i32_e32 v4, 31, v3
	v_lshrrev_b32_e32 v4, 26, v4
	v_add_u32_e32 v10, v3, v4
	v_ashrrev_i32_e32 v8, 6, v10
	v_ashrrev_i32_e32 v9, 31, v8
	v_lshlrev_b32_e32 v6, 9, v8
	v_lshlrev_b64 v[4:5], 10, v[8:9]
	v_sub_u32_e32 v6, v2, v6
	v_lshl_add_u64 v[4:5], s[14:15], 0, v[4:5]
	v_ashrrev_i32_e32 v7, 31, v6
	v_lshl_add_u64 v[4:5], v[6:7], 1, v[4:5]
	global_load_dwordx4 v[104:107], v[4:5], off
	v_and_b32_e32 v10, 0xfffffc0, v10
	v_sub_u32_e32 v10, v3, v10
	v_lshlrev_b32_e32 v11, 10, v8
	v_bitop3_b32 v8, v8, v10, 15 bitop3:0x6c
	v_add_u32_e32 v9, 0x200, v3
	v_lshlrev_b32_e32 v8, 4, v8
	v_mov_b32_e32 v3, v9
	v_add_u32_e32 v2, 0x1000, v2
	v_add3_u32 v46, 16, v11, v8
	v_ashrrev_i32_e32 v4, 31, v3
	v_lshrrev_b32_e32 v4, 26, v4
	v_add_u32_e32 v10, v3, v4
	v_ashrrev_i32_e32 v8, 6, v10
	v_ashrrev_i32_e32 v9, 31, v8
	v_lshlrev_b32_e32 v6, 9, v8
	v_lshlrev_b64 v[4:5], 10, v[8:9]
	v_sub_u32_e32 v6, v2, v6
	v_lshl_add_u64 v[4:5], s[14:15], 0, v[4:5]
	v_ashrrev_i32_e32 v7, 31, v6
	v_lshl_add_u64 v[4:5], v[6:7], 1, v[4:5]
	global_load_dwordx4 v[108:111], v[4:5], off
	v_and_b32_e32 v10, 0xfffffc0, v10
	v_sub_u32_e32 v10, v3, v10
	v_lshlrev_b32_e32 v11, 10, v8
	v_bitop3_b32 v8, v8, v10, 15 bitop3:0x6c
	v_add_u32_e32 v9, 0x200, v3
	v_lshlrev_b32_e32 v8, 4, v8
	v_mov_b32_e32 v3, v9
	v_add_u32_e32 v2, 0x1000, v2
	v_add3_u32 v47, 16, v11, v8
	v_ashrrev_i32_e32 v4, 31, v3
	v_lshrrev_b32_e32 v4, 26, v4
	v_add_u32_e32 v10, v3, v4
	v_ashrrev_i32_e32 v8, 6, v10
	v_ashrrev_i32_e32 v9, 31, v8
	v_lshlrev_b32_e32 v6, 9, v8
	v_lshlrev_b64 v[4:5], 10, v[8:9]
	v_sub_u32_e32 v6, v2, v6
	v_lshl_add_u64 v[4:5], s[14:15], 0, v[4:5]
; #define LAS __attribute__((address_space(3)))
; template <int KW, bool YST>
; __device__ __forceinline__ void ssm_stage_lds(PREF P, const int l, const int wi, unsigned char* shm, const int tid) {
;     ...
;     for (int ch = tid; ch < 128 * CPR; ch += 512) { const int row = ch / CPR, c = ch % CPR; const u32x4 v = *(const u32x4*)(D + (size_t)row * KW + c * 8);
;         *(LAS u32x4*)(lds + row * (KW * 2) + ((c ^ (row & 15)) << 4)) = v; }
;     __syncthreads();
	v_ashrrev_i32_e32 v7, 31, v6
	v_lshl_add_u64 v[4:5], v[6:7], 1, v[4:5]
	global_load_dwordx4 v[112:115], v[4:5], off
	v_and_b32_e32 v10, 0xfffffc0, v10
	v_sub_u32_e32 v10, v3, v10
	v_lshlrev_b32_e32 v11, 10, v8
	v_bitop3_b32 v8, v8, v10, 15 bitop3:0x6c
	v_add_u32_e32 v9, 0x200, v3
	v_lshlrev_b32_e32 v8, 4, v8
	v_mov_b32_e32 v3, v9
	v_add_u32_e32 v2, 0x1000, v2
	v_add3_u32 v48, 16, v11, v8
	v_ashrrev_i32_e32 v4, 31, v3
	v_lshrrev_b32_e32 v4, 26, v4
	v_add_u32_e32 v10, v3, v4
	v_ashrrev_i32_e32 v8, 6, v10
	v_ashrrev_i32_e32 v9, 31, v8
	v_lshlrev_b32_e32 v6, 9, v8
	v_lshlrev_b64 v[4:5], 10, v[8:9]
	v_sub_u32_e32 v6, v2, v6
	v_lshl_add_u64 v[4:5], s[14:15], 0, v[4:5]
	v_ashrrev_i32_e32 v7, 31, v6
	v_lshl_add_u64 v[4:5], v[6:7], 1, v[4:5]
	global_load_dwordx4 v[116:119], v[4:5], off
	v_and_b32_e32 v10, 0xfffffc0, v10
	v_sub_u32_e32 v10, v3, v10
	v_lshlrev_b32_e32 v11, 10, v8
	v_bitop3_b32 v8, v8, v10, 15 bitop3:0x6c
	v_add_u32_e32 v9, 0x200, v3
	v_lshlrev_b32_e32 v8, 4, v8
	v_mov_b32_e32 v3, v9
	v_add_u32_e32 v2, 0x1000, v2
	v_add3_u32 v49, 16, v11, v8
	v_ashrrev_i32_e32 v4, 31, v3
	v_lshrrev_b32_e32 v4, 26, v4
	v_add_u32_e32 v10, v3, v4
	v_ashrrev_i32_e32 v8, 6, v10
	v_ashrrev_i32_e32 v9, 31, v8
	v_lshlrev_b32_e32 v6, 9, v8
	v_lshlrev_b64 v[4:5], 10, v[8:9]
	v_sub_u32_e32 v6, v2, v6
	v_lshl_add_u64 v[4:5], s[14:15], 0, v[4:5]
	v_ashrrev_i32_e32 v7, 31, v6
	v_lshl_add_u64 v[4:5], v[6:7], 1, v[4:5]
	global_load_dwordx4 v[120:123], v[4:5], off
	v_and_b32_e32 v10, 0xfffffc0, v10
	v_sub_u32_e32 v10, v3, v10
	v_lshlrev_b32_e32 v11, 10, v8
	v_bitop3_b32 v8, v8, v10, 15 bitop3:0x6c
	v_add_u32_e32 v9, 0x200, v3
	v_lshlrev_b32_e32 v8, 4, v8
	v_mov_b32_e32 v3, v9
	v_add_u32_e32 v2, 0x1000, v2
	v_add3_u32 v50, 16, v11, v8
	v_ashrrev_i32_e32 v4, 31, v3
	v_lshrrev_b32_e32 v4, 26, v4
	v_add_u32_e32 v10, v3, v4
	v_ashrrev_i32_e32 v8, 6, v10
	v_ashrrev_i32_e32 v9, 31, v8
	v_lshlrev_b32_e32 v6, 9, v8
	v_lshlrev_b64 v[4:5], 10, v[8:9]
	v_sub_u32_e32 v6, v2, v6
	v_lshl_add_u64 v[4:5], s[14:15], 0, v[4:5]
	v_ashrrev_i32_e32 v7, 31, v6
	v_lshl_add_u64 v[4:5], v[6:7], 1, v[4:5]
	global_load_dwordx4 v[124:127], v[4:5], off
	v_and_b32_e32 v10, 0xfffffc0, v10
	v_sub_u32_e32 v10, v3, v10
	v_lshlrev_b32_e32 v11, 10, v8
	v_bitop3_b32 v8, v8, v10, 15 bitop3:0x6c
	v_add_u32_e32 v9, 0x200, v3
	v_lshlrev_b32_e32 v8, 4, v8
	v_mov_b32_e32 v3, v9
	v_add_u32_e32 v2, 0x1000, v2
	v_add3_u32 v51, 16, v11, v8
	v_ashrrev_i32_e32 v4, 31, v3
	v_lshrrev_b32_e32 v4, 26, v4
	v_add_u32_e32 v10, v3, v4
	v_ashrrev_i32_e32 v8, 6, v10
	v_ashrrev_i32_e32 v9, 31, v8
	v_lshlrev_b32_e32 v6, 9, v8
	v_lshlrev_b64 v[4:5], 10, v[8:9]
	v_sub_u32_e32 v6, v2, v6
	v_lshl_add_u64 v[4:5], s[14:15], 0, v[4:5]
	v_ashrrev_i32_e32 v7, 31, v6
	v_lshl_add_u64 v[4:5], v[6:7], 1, v[4:5]
	global_load_dwordx4 v[128:131], v[4:5], off
	v_and_b32_e32 v10, 0xfffffc0, v10
	v_sub_u32_e32 v10, v3, v10
	v_lshlrev_b32_e32 v11, 10, v8
	v_bitop3_b32 v8, v8, v10, 15 bitop3:0x6c
	v_add_u32_e32 v9, 0x200, v3
	v_lshlrev_b32_e32 v8, 4, v8
	v_mov_b32_e32 v3, v9
	v_add_u32_e32 v2, 0x1000, v2
	v_add3_u32 v52, 16, v11, v8
	v_ashrrev_i32_e32 v4, 31, v3
	v_lshrrev_b32_e32 v4, 26, v4
	v_add_u32_e32 v10, v3, v4
	v_ashrrev_i32_e32 v8, 6, v10
	v_ashrrev_i32_e32 v9, 31, v8
	v_lshlrev_b32_e32 v6, 9, v8
	v_lshlrev_b64 v[4:5], 10, v[8:9]
	v_sub_u32_e32 v6, v2, v6
	v_lshl_add_u64 v[4:5], s[14:15], 0, v[4:5]
	v_ashrrev_i32_e32 v7, 31, v6
	v_lshl_add_u64 v[4:5], v[6:7], 1, v[4:5]
	global_load_dwordx4 v[132:135], v[4:5], off
	v_and_b32_e32 v10, 0xfffffc0, v10
	v_sub_u32_e32 v10, v3, v10
	v_lshlrev_b32_e32 v11, 10, v8
	v_bitop3_b32 v8, v8, v10, 15 bitop3:0x6c
	v_add_u32_e32 v9, 0x200, v3
	v_lshlrev_b32_e32 v8, 4, v8
	v_mov_b32_e32 v3, v9
	v_add_u32_e32 v2, 0x1000, v2
	v_add3_u32 v53, 16, v11, v8
	v_ashrrev_i32_e32 v4, 31, v3
	v_lshrrev_b32_e32 v4, 26, v4
	v_add_u32_e32 v10, v3, v4
	v_ashrrev_i32_e32 v8, 6, v10
	v_ashrrev_i32_e32 v9, 31, v8
	v_lshlrev_b32_e32 v6, 9, v8
	v_lshlrev_b64 v[4:5], 10, v[8:9]
	v_sub_u32_e32 v6, v2, v6
	v_lshl_add_u64 v[4:5], s[14:15], 0, v[4:5]
	v_ashrrev_i32_e32 v7, 31, v6
	v_lshl_add_u64 v[4:5], v[6:7], 1, v[4:5]
	global_load_dwordx4 v[136:139], v[4:5], off
	v_and_b32_e32 v10, 0xfffffc0, v10
	v_sub_u32_e32 v10, v3, v10
	v_lshlrev_b32_e32 v11, 10, v8
	v_bitop3_b32 v8, v8, v10, 15 bitop3:0x6c
	v_add_u32_e32 v9, 0x200, v3
	v_lshlrev_b32_e32 v8, 4, v8
	v_mov_b32_e32 v3, v9
	v_add_u32_e32 v2, 0x1000, v2
	v_add3_u32 v54, 16, v11, v8
	v_ashrrev_i32_e32 v4, 31, v3
	v_lshrrev_b32_e32 v4, 26, v4
	v_add_u32_e32 v10, v3, v4
	v_ashrrev_i32_e32 v8, 6, v10
	v_ashrrev_i32_e32 v9, 31, v8
	v_lshlrev_b32_e32 v6, 9, v8
	v_lshlrev_b64 v[4:5], 10, v[8:9]
	v_sub_u32_e32 v6, v2, v6
	v_lshl_add_u64 v[4:5], s[14:15], 0, v[4:5]
	v_ashrrev_i32_e32 v7, 31, v6
	v_lshl_add_u64 v[4:5], v[6:7], 1, v[4:5]
	global_load_dwordx4 v[140:143], v[4:5], off
	v_and_b32_e32 v10, 0xfffffc0, v10
	v_sub_u32_e32 v10, v3, v10
	v_lshlrev_b32_e32 v11, 10, v8
	v_bitop3_b32 v8, v8, v10, 15 bitop3:0x6c
	v_add_u32_e32 v9, 0x200, v3
	v_lshlrev_b32_e32 v8, 4, v8
	v_mov_b32_e32 v3, v9
	v_add_u32_e32 v2, 0x1000, v2
	v_add3_u32 v55, 16, v11, v8
	s_waitcnt vmcnt(15)
	ds_write_b128 v40, v[80:83]
	s_waitcnt vmcnt(14)
	ds_write_b128 v41, v[84:87]
	s_waitcnt vmcnt(13)
	ds_write_b128 v42, v[88:91]
	s_waitcnt vmcnt(12)
	ds_write_b128 v43, v[92:95]
	s_waitcnt vmcnt(11)
	ds_write_b128 v44, v[96:99]
	s_waitcnt vmcnt(10)
	ds_write_b128 v45, v[100:103]
	s_waitcnt vmcnt(9)
	ds_write_b128 v46, v[104:107]
	s_waitcnt vmcnt(8)
	ds_write_b128 v47, v[108:111]
	s_waitcnt vmcnt(7)
	ds_write_b128 v48, v[112:115]
	s_waitcnt vmcnt(6)
	ds_write_b128 v49, v[116:119]
	s_waitcnt vmcnt(5)
	ds_write_b128 v50, v[120:123]
	s_waitcnt vmcnt(4)
	ds_write_b128 v51, v[124:127]
	s_waitcnt vmcnt(3)
	ds_write_b128 v52, v[128:131]
	s_waitcnt vmcnt(2)
	ds_write_b128 v53, v[132:135]
	s_waitcnt vmcnt(1)
	ds_write_b128 v54, v[136:139]
	s_waitcnt vmcnt(0)
	ds_write_b128 v55, v[140:143]

; #define LAS __attribute__((address_space(3)))
; template <int KW, bool YST>
; __device__ __forceinline__ void ssm_stage_lds(PREF P, const int l, const int wi, unsigned char* shm, const int tid) {
;     ...
;     for (int ch = tid; ch < 128 * CPR; ch += 512) { const int row = ch / CPR, c = ch % CPR; const u32x4 v = *(const u32x4*)(D + (size_t)row * KW + c * 8);
;         *(LAS u32x4*)(lds + row * (KW * 2) + ((c ^ (row & 15)) << 4)) = v; }
.LBB0_1315:
	v_ashrrev_i32_e32 v4, 31, v3
	v_lshrrev_b32_e32 v4, 26, v4
	v_add_u32_e32 v10, v3, v4
	v_ashrrev_i32_e32 v8, 6, v10
	v_ashrrev_i32_e32 v9, 31, v8
	v_lshlrev_b32_e32 v6, 9, v8
	v_lshlrev_b64 v[4:5], 10, v[8:9]
	v_sub_u32_e32 v6, v2, v6
	v_lshl_add_u64 v[4:5], s[18:19], 0, v[4:5]
	v_ashrrev_i32_e32 v7, 31, v6
	v_lshl_add_u64 v[4:5], v[6:7], 1, v[4:5]
	global_load_dwordx4 v[80:83], v[4:5], off
	v_and_b32_e32 v10, 0xfffffc0, v10
	v_sub_u32_e32 v10, v3, v10
	v_lshlrev_b32_e32 v11, 10, v8
	v_bitop3_b32 v8, v8, v10, 15 bitop3:0x6c
	v_add_u32_e32 v9, 0x200, v3
	v_lshlrev_b32_e32 v8, 4, v8
	v_mov_b32_e32 v3, v9
	v_add_u32_e32 v2, 0x1000, v2
	v_add3_u32 v40, 16, v11, v8
	v_ashrrev_i32_e32 v4, 31, v3
	v_lshrrev_b32_e32 v4, 26, v4
	v_add_u32_e32 v10, v3, v4
	v_ashrrev_i32_e32 v8, 6, v10
	v_ashrrev_i32_e32 v9, 31, v8
	v_lshlrev_b32_e32 v6, 9, v8
	v_lshlrev_b64 v[4:5], 10, v[8:9]
	v_sub_u32_e32 v6, v2, v6
	v_lshl_add_u64 v[4:5], s[18:19], 0, v[4:5]
	v_ashrrev_i32_e32 v7, 31, v6
	v_lshl_add_u64 v[4:5], v[6:7], 1, v[4:5]
	global_load_dwordx4 v[84:87], v[4:5], off
	v_and_b32_e32 v10, 0xfffffc0, v10
	v_sub_u32_e32 v10, v3, v10
	v_lshlrev_b32_e32 v11, 10, v8
	v_bitop3_b32 v8, v8, v10, 15 bitop3:0x6c
	v_add_u32_e32 v9, 0x200, v3
	v_lshlrev_b32_e32 v8, 4, v8
	v_mov_b32_e32 v3, v9
	v_add_u32_e32 v2, 0x1000, v2
	v_add3_u32 v41, 16, v11, v8
	v_ashrrev_i32_e32 v4, 31, v3
	v_lshrrev_b32_e32 v4, 26, v4
	v_add_u32_e32 v10, v3, v4
	v_ashrrev_i32_e32 v8, 6, v10
	v_ashrrev_i32_e32 v9, 31, v8
	v_lshlrev_b32_e32 v6, 9, v8
	v_lshlrev_b64 v[4:5], 10, v[8:9]
	v_sub_u32_e32 v6, v2, v6
	v_lshl_add_u64 v[4:5], s[18:19], 0, v[4:5]
	v_ashrrev_i32_e32 v7, 31, v6
	v_lshl_add_u64 v[4:5], v[6:7], 1, v[4:5]
	global_load_dwordx4 v[88:91], v[4:5], off
	v_and_b32_e32 v10, 0xfffffc0, v10
	v_sub_u32_e32 v10, v3, v10
	v_lshlrev_b32_e32 v11, 10, v8
	v_bitop3_b32 v8, v8, v10, 15 bitop3:0x6c
	v_add_u32_e32 v9, 0x200, v3
	v_lshlrev_b32_e32 v8, 4, v8
	v_mov_b32_e32 v3, v9
	v_add_u32_e32 v2, 0x1000, v2
	v_add3_u32 v42, 16, v11, v8
	v_ashrrev_i32_e32 v4, 31, v3
	v_lshrrev_b32_e32 v4, 26, v4
	v_add_u32_e32 v10, v3, v4
	v_ashrrev_i32_e32 v8, 6, v10
	v_ashrrev_i32_e32 v9, 31, v8
	v_lshlrev_b32_e32 v6, 9, v8
	v_lshlrev_b64 v[4:5], 10, v[8:9]
	v_sub_u32_e32 v6, v2, v6
	v_lshl_add_u64 v[4:5], s[18:19], 0, v[4:5]
	v_ashrrev_i32_e32 v7, 31, v6
	v_lshl_add_u64 v[4:5], v[6:7], 1, v[4:5]
	global_load_dwordx4 v[92:95], v[4:5], off
	v_and_b32_e32 v10, 0xfffffc0, v10
	v_sub_u32_e32 v10, v3, v10
	v_lshlrev_b32_e32 v11, 10, v8
	v_bitop3_b32 v8, v8, v10, 15 bitop3:0x6c
	v_add_u32_e32 v9, 0x200, v3
	v_lshlrev_b32_e32 v8, 4, v8
	v_mov_b32_e32 v3, v9
	v_add_u32_e32 v2, 0x1000, v2
	v_add3_u32 v43, 16, v11, v8
	v_ashrrev_i32_e32 v4, 31, v3
	v_lshrrev_b32_e32 v4, 26, v4
	v_add_u32_e32 v10, v3, v4
	v_ashrrev_i32_e32 v8, 6, v10
	v_ashrrev_i32_e32 v9, 31, v8
	v_lshlrev_b32_e32 v6, 9, v8
	v_lshlrev_b64 v[4:5], 10, v[8:9]
	v_sub_u32_e32 v6, v2, v6
	v_lshl_add_u64 v[4:5], s[18:19], 0, v[4:5]
	v_ashrrev_i32_e32 v7, 31, v6
	v_lshl_add_u64 v[4:5], v[6:7], 1, v[4:5]
	global_load_dwordx4 v[96:99], v[4:5], off
	v_and_b32_e32 v10, 0xfffffc0, v10
	v_sub_u32_e32 v10, v3, v10
	v_lshlrev_b32_e32 v11, 10, v8
	v_bitop3_b32 v8, v8, v10, 15 bitop3:0x6c
	v_add_u32_e32 v9, 0x200, v3
	v_lshlrev_b32_e32 v8, 4, v8
	v_mov_b32_e32 v3, v9
	v_add_u32_e32 v2, 0x1000, v2
	v_add3_u32 v44, 16, v11, v8
	v_ashrrev_i32_e32 v4, 31, v3
	v_lshrrev_b32_e32 v4, 26, v4
	v_add_u32_e32 v10, v3, v4
	v_ashrrev_i32_e32 v8, 6, v10
	v_ashrrev_i32_e32 v9, 31, v8
	v_lshlrev_b32_e32 v6, 9, v8
	v_lshlrev_b64 v[4:5], 10, v[8:9]
	v_sub_u32_e32 v6, v2, v6
	v_lshl_add_u64 v[4:5], s[18:19], 0, v[4:5]
	v_ashrrev_i32_e32 v7, 31, v6
	v_lshl_add_u64 v[4:5], v[6:7], 1, v[4:5]
	global_load_dwordx4 v[100:103], v[4:5], off
	v_and_b32_e32 v10, 0xfffffc0, v10
	v_sub_u32_e32 v10, v3, v10
	v_lshlrev_b32_e32 v11, 10, v8
	v_bitop3_b32 v8, v8, v10, 15 bitop3:0x6c
	v_add_u32_e32 v9, 0x200, v3
	v_lshlrev_b32_e32 v8, 4, v8
	v_mov_b32_e32 v3, v9
	v_add_u32_e32 v2, 0x1000, v2
	v_add3_u32 v45, 16, v11, v8
	v_ashrrev_i32_e32 v4, 31, v3
	v_lshrrev_b32_e32 v4, 26, v4
	v_add_u32_e32 v10, v3, v4
	v_ashrrev_i32_e32 v8, 6, v10
	v_ashrrev_i32_e32 v9, 31, v8
	v_lshlrev_b32_e32 v6, 9, v8
	v_lshlrev_b64 v[4:5], 10, v[8:9]
	v_sub_u32_e32 v6, v2, v6
	v_lshl_add_u64 v[4:5], s[18:19], 0, v[4:5]
	v_ashrrev_i32_e32 v7, 31, v6
	v_lshl_add_u64 v[4:5], v[6:7], 1, v[4:5]
	global_load_dwordx4 v[104:107], v[4:5], off
	v_and_b32_e32 v10, 0xfffffc0, v10
	v_sub_u32_e32 v10, v3, v10
	v_lshlrev_b32_e32 v11, 10, v8
	v_bitop3_b32 v8, v8, v10, 15 bitop3:0x6c
	v_add_u32_e32 v9, 0x200, v3
	v_lshlrev_b32_e32 v8, 4, v8
	v_mov_b32_e32 v3, v9
	v_add_u32_e32 v2, 0x1000, v2
	v_add3_u32 v46, 16, v11, v8
	v_ashrrev_i32_e32 v4, 31, v3
	v_lshrrev_b32_e32 v4, 26, v4
	v_add_u32_e32 v10, v3, v4
	v_ashrrev_i32_e32 v8, 6, v10
	v_ashrrev_i32_e32 v9, 31, v8
	v_lshlrev_b32_e32 v6, 9, v8
	v_lshlrev_b64 v[4:5], 10, v[8:9]
	v_sub_u32_e32 v6, v2, v6
	v_lshl_add_u64 v[4:5], s[18:19], 0, v[4:5]
	v_ashrrev_i32_e32 v7, 31, v6
	v_lshl_add_u64 v[4:5], v[6:7], 1, v[4:5]
	global_load_dwordx4 v[108:111], v[4:5], off
	v_and_b32_e32 v10, 0xfffffc0, v10
	v_sub_u32_e32 v10, v3, v10
	v_lshlrev_b32_e32 v11, 10, v8
	v_bitop3_b32 v8, v8, v10, 15 bitop3:0x6c
	v_add_u32_e32 v9, 0x200, v3
	v_lshlrev_b32_e32 v8, 4, v8
	v_mov_b32_e32 v3, v9
	v_add_u32_e32 v2, 0x1000, v2
	v_add3_u32 v47, 16, v11, v8
	v_ashrrev_i32_e32 v4, 31, v3
	v_lshrrev_b32_e32 v4, 26, v4
	v_add_u32_e32 v10, v3, v4
	v_ashrrev_i32_e32 v8, 6, v10
	v_ashrrev_i32_e32 v9, 31, v8
	v_lshlrev_b32_e32 v6, 9, v8
	v_lshlrev_b64 v[4:5], 10, v[8:9]
	v_sub_u32_e32 v6, v2, v6
	v_lshl_add_u64 v[4:5], s[18:19], 0, v[4:5]
; #define LAS __attribute__((address_space(3)))
; template <int KW, bool YST>
; __device__ __forceinline__ void ssm_stage_lds(PREF P, const int l, const int wi, unsigned char* shm, const int tid) {
;     ...
;     for (int ch = tid; ch < 128 * CPR; ch += 512) { const int row = ch / CPR, c = ch % CPR; const u32x4 v = *(const u32x4*)(D + (size_t)row * KW + c * 8);
;         *(LAS u32x4*)(lds + row * (KW * 2) + ((c ^ (row & 15)) << 4)) = v; }
;     __syncthreads();
	v_ashrrev_i32_e32 v7, 31, v6
	v_lshl_add_u64 v[4:5], v[6:7], 1, v[4:5]
	global_load_dwordx4 v[112:115], v[4:5], off
	v_and_b32_e32 v10, 0xfffffc0, v10
	v_sub_u32_e32 v10, v3, v10
	v_lshlrev_b32_e32 v11, 10, v8
	v_bitop3_b32 v8, v8, v10, 15 bitop3:0x6c
	v_add_u32_e32 v9, 0x200, v3
	v_lshlrev_b32_e32 v8, 4, v8
	v_mov_b32_e32 v3, v9
	v_add_u32_e32 v2, 0x1000, v2
	v_add3_u32 v48, 16, v11, v8
	v_ashrrev_i32_e32 v4, 31, v3
	v_lshrrev_b32_e32 v4, 26, v4
	v_add_u32_e32 v10, v3, v4
	v_ashrrev_i32_e32 v8, 6, v10
	v_ashrrev_i32_e32 v9, 31, v8
	v_lshlrev_b32_e32 v6, 9, v8
	v_lshlrev_b64 v[4:5], 10, v[8:9]
	v_sub_u32_e32 v6, v2, v6
	v_lshl_add_u64 v[4:5], s[18:19], 0, v[4:5]
	v_ashrrev_i32_e32 v7, 31, v6
	v_lshl_add_u64 v[4:5], v[6:7], 1, v[4:5]
	global_load_dwordx4 v[116:119], v[4:5], off
	v_and_b32_e32 v10, 0xfffffc0, v10
	v_sub_u32_e32 v10, v3, v10
	v_lshlrev_b32_e32 v11, 10, v8
	v_bitop3_b32 v8, v8, v10, 15 bitop3:0x6c
	v_add_u32_e32 v9, 0x200, v3
	v_lshlrev_b32_e32 v8, 4, v8
	v_mov_b32_e32 v3, v9
	v_add_u32_e32 v2, 0x1000, v2
	v_add3_u32 v49, 16, v11, v8
	v_ashrrev_i32_e32 v4, 31, v3
	v_lshrrev_b32_e32 v4, 26, v4
	v_add_u32_e32 v10, v3, v4
	v_ashrrev_i32_e32 v8, 6, v10
	v_ashrrev_i32_e32 v9, 31, v8
	v_lshlrev_b32_e32 v6, 9, v8
	v_lshlrev_b64 v[4:5], 10, v[8:9]
	v_sub_u32_e32 v6, v2, v6
	v_lshl_add_u64 v[4:5], s[18:19], 0, v[4:5]
	v_ashrrev_i32_e32 v7, 31, v6
	v_lshl_add_u64 v[4:5], v[6:7], 1, v[4:5]
	global_load_dwordx4 v[120:123], v[4:5], off
	v_and_b32_e32 v10, 0xfffffc0, v10
	v_sub_u32_e32 v10, v3, v10
	v_lshlrev_b32_e32 v11, 10, v8
	v_bitop3_b32 v8, v8, v10, 15 bitop3:0x6c
	v_add_u32_e32 v9, 0x200, v3
	v_lshlrev_b32_e32 v8, 4, v8
	v_mov_b32_e32 v3, v9
	v_add_u32_e32 v2, 0x1000, v2
	v_add3_u32 v50, 16, v11, v8
	v_ashrrev_i32_e32 v4, 31, v3
	v_lshrrev_b32_e32 v4, 26, v4
	v_add_u32_e32 v10, v3, v4
	v_ashrrev_i32_e32 v8, 6, v10
	v_ashrrev_i32_e32 v9, 31, v8
	v_lshlrev_b32_e32 v6, 9, v8
	v_lshlrev_b64 v[4:5], 10, v[8:9]
	v_sub_u32_e32 v6, v2, v6
	v_lshl_add_u64 v[4:5], s[18:19], 0, v[4:5]
	v_ashrrev_i32_e32 v7, 31, v6
	v_lshl_add_u64 v[4:5], v[6:7], 1, v[4:5]
	global_load_dwordx4 v[124:127], v[4:5], off
	v_and_b32_e32 v10, 0xfffffc0, v10
	v_sub_u32_e32 v10, v3, v10
	v_lshlrev_b32_e32 v11, 10, v8
	v_bitop3_b32 v8, v8, v10, 15 bitop3:0x6c
	v_add_u32_e32 v9, 0x200, v3
	v_lshlrev_b32_e32 v8, 4, v8
	v_mov_b32_e32 v3, v9
	v_add_u32_e32 v2, 0x1000, v2
	v_add3_u32 v51, 16, v11, v8
	v_ashrrev_i32_e32 v4, 31, v3
	v_lshrrev_b32_e32 v4, 26, v4
	v_add_u32_e32 v10, v3, v4
	v_ashrrev_i32_e32 v8, 6, v10
	v_ashrrev_i32_e32 v9, 31, v8
	v_lshlrev_b32_e32 v6, 9, v8
	v_lshlrev_b64 v[4:5], 10, v[8:9]
	v_sub_u32_e32 v6, v2, v6
	v_lshl_add_u64 v[4:5], s[18:19], 0, v[4:5]
	v_ashrrev_i32_e32 v7, 31, v6
	v_lshl_add_u64 v[4:5], v[6:7], 1, v[4:5]
	global_load_dwordx4 v[128:131], v[4:5], off
	v_and_b32_e32 v10, 0xfffffc0, v10
	v_sub_u32_e32 v10, v3, v10
	v_lshlrev_b32_e32 v11, 10, v8
	v_bitop3_b32 v8, v8, v10, 15 bitop3:0x6c
	v_add_u32_e32 v9, 0x200, v3
	v_lshlrev_b32_e32 v8, 4, v8
	v_mov_b32_e32 v3, v9
	v_add_u32_e32 v2, 0x1000, v2
	v_add3_u32 v52, 16, v11, v8
	v_ashrrev_i32_e32 v4, 31, v3
	v_lshrrev_b32_e32 v4, 26, v4
	v_add_u32_e32 v10, v3, v4
	v_ashrrev_i32_e32 v8, 6, v10
	v_ashrrev_i32_e32 v9, 31, v8
	v_lshlrev_b32_e32 v6, 9, v8
	v_lshlrev_b64 v[4:5], 10, v[8:9]
	v_sub_u32_e32 v6, v2, v6
	v_lshl_add_u64 v[4:5], s[18:19], 0, v[4:5]
	v_ashrrev_i32_e32 v7, 31, v6
	v_lshl_add_u64 v[4:5], v[6:7], 1, v[4:5]
	global_load_dwordx4 v[132:135], v[4:5], off
	v_and_b32_e32 v10, 0xfffffc0, v10
	v_sub_u32_e32 v10, v3, v10
	v_lshlrev_b32_e32 v11, 10, v8
	v_bitop3_b32 v8, v8, v10, 15 bitop3:0x6c
	v_add_u32_e32 v9, 0x200, v3
	v_lshlrev_b32_e32 v8, 4, v8
	v_mov_b32_e32 v3, v9
	v_add_u32_e32 v2, 0x1000, v2
	v_add3_u32 v53, 16, v11, v8
	v_ashrrev_i32_e32 v4, 31, v3
	v_lshrrev_b32_e32 v4, 26, v4
	v_add_u32_e32 v10, v3, v4
	v_ashrrev_i32_e32 v8, 6, v10
	v_ashrrev_i32_e32 v9, 31, v8
	v_lshlrev_b32_e32 v6, 9, v8
	v_lshlrev_b64 v[4:5], 10, v[8:9]
	v_sub_u32_e32 v6, v2, v6
	v_lshl_add_u64 v[4:5], s[18:19], 0, v[4:5]
	v_ashrrev_i32_e32 v7, 31, v6
	v_lshl_add_u64 v[4:5], v[6:7], 1, v[4:5]
	global_load_dwordx4 v[136:139], v[4:5], off
	v_and_b32_e32 v10, 0xfffffc0, v10
	v_sub_u32_e32 v10, v3, v10
	v_lshlrev_b32_e32 v11, 10, v8
	v_bitop3_b32 v8, v8, v10, 15 bitop3:0x6c
	v_add_u32_e32 v9, 0x200, v3
	v_lshlrev_b32_e32 v8, 4, v8
	v_mov_b32_e32 v3, v9
	v_add_u32_e32 v2, 0x1000, v2
	v_add3_u32 v54, 16, v11, v8
	v_ashrrev_i32_e32 v4, 31, v3
	v_lshrrev_b32_e32 v4, 26, v4
	v_add_u32_e32 v10, v3, v4
	v_ashrrev_i32_e32 v8, 6, v10
	v_ashrrev_i32_e32 v9, 31, v8
	v_lshlrev_b32_e32 v6, 9, v8
	v_lshlrev_b64 v[4:5], 10, v[8:9]
	v_sub_u32_e32 v6, v2, v6
	v_lshl_add_u64 v[4:5], s[18:19], 0, v[4:5]
	v_ashrrev_i32_e32 v7, 31, v6
	v_lshl_add_u64 v[4:5], v[6:7], 1, v[4:5]
	global_load_dwordx4 v[140:143], v[4:5], off
	v_and_b32_e32 v10, 0xfffffc0, v10
	v_sub_u32_e32 v10, v3, v10
	v_lshlrev_b32_e32 v11, 10, v8
	v_bitop3_b32 v8, v8, v10, 15 bitop3:0x6c
	v_add_u32_e32 v9, 0x200, v3
	v_lshlrev_b32_e32 v8, 4, v8
	v_mov_b32_e32 v3, v9
	v_add_u32_e32 v2, 0x1000, v2
	v_add3_u32 v55, 16, v11, v8
	s_waitcnt vmcnt(15)
	ds_write_b128 v40, v[80:83]
	s_waitcnt vmcnt(14)
	ds_write_b128 v41, v[84:87]
	s_waitcnt vmcnt(13)
	ds_write_b128 v42, v[88:91]
	s_waitcnt vmcnt(12)
	ds_write_b128 v43, v[92:95]
	s_waitcnt vmcnt(11)
	ds_write_b128 v44, v[96:99]
	s_waitcnt vmcnt(10)
	ds_write_b128 v45, v[100:103]
	s_waitcnt vmcnt(9)
	ds_write_b128 v46, v[104:107]
	s_waitcnt vmcnt(8)
	ds_write_b128 v47, v[108:111]
	s_waitcnt vmcnt(7)
	ds_write_b128 v48, v[112:115]
	s_waitcnt vmcnt(6)
	ds_write_b128 v49, v[116:119]
	s_waitcnt vmcnt(5)
	ds_write_b128 v50, v[120:123]
	s_waitcnt vmcnt(4)
	ds_write_b128 v51, v[124:127]
	s_waitcnt vmcnt(3)
	ds_write_b128 v52, v[128:131]
	s_waitcnt vmcnt(2)
	ds_write_b128 v53, v[132:135]
	s_waitcnt vmcnt(1)
	ds_write_b128 v54, v[136:139]
	s_waitcnt vmcnt(0)
	ds_write_b128 v55, v[140:143]
